# GEMM units (P1,P2,P4,P11,P12): the first load segment's 16 ds_reads are issued before the 128 accumulator-zeroing moves and the K-loop is entered past them
# speedup vs baseline: 1.0016x; 1.0016x over previous
; #define PG8_STAGE(bufoff, gbase, voff) do { _Pragma("unroll") for (int _i = 0; _i < 2; ++_i) \
;         __builtin_amdgcn_global_load_lds((const unsigned*)((const char*)(gbase) + (voff)[_i]), (PG8_LAS unsigned*)(lds + (bufoff) + ldsw + _i * 8192), 16, 0, 0); } while (0)
; #define PG8_LDA(dst, b, h) do { _Pragma("unroll") for (int m = 0; m < 4; ++m) _Pragma("unroll") for (int k = 0; k < 2; ++k) dst[m][k] = *(const PG8_LAS bf16x8*)(lds + PG8_SA(b, h) + aoff + m * 2048 + k * 1024); } while (0)
; #define PG8_LDB(dst, b, h) do { _Pragma("unroll") for (int n = 0; n < 2; ++n) _Pragma("unroll") for (int k = 0; k < 2; ++k) dst[n][k] = *(const PG8_LAS bf16x8*)(lds + PG8_SB(b, h) + boff + n * 2048 + k * 1024); } while (0)
; #define PG8_SCHED __builtin_amdgcn_sched_barrier(0)
; template <class Epi, class Sched, bool ALIGN_EPI = false, bool SP2 = false>
; __device__ __forceinline__ void gemm_phase(PG8_LAS unsigned char* lds, const Gemm g, const Sched& S, const Epi& E) {
;     ...
;         const bool has_next = S.next(ui + 1, nxt);
;         const char* nA = has_next ? (const char*)g.A + (size_t)nxt.pm * tstep : cA; const char* nB = has_next ? (const char*)g.Bt + (size_t)nxt.pn * tstep : cB;
;         for (int t = 0; t < nt; t += 2) {
;             const bool last = (t == nt - 2);
;             const char* a1 = cA + (size_t)(t + 1) * kstep;
;             const char* a2 = last ? nA : cA + (size_t)(t + 2) * kstep; const char* b2 = last ? nB : cB + (size_t)(t + 2) * kstep;
;             const char* a3 = a2 + kstep; const char* b3 = b2 + kstep;
;             if (last && has_next) S.a_ready(nxt);
;             if constexpr (SP2) {
;             PG8_LDB(B0, 0, 0); PG8_LDB(B1, 0, 1); PG8_SCHED; PG8_LDA(At, 0, 0); PG8_STAGE(PG8_SA(1, 1), a1 + hstep, voffA);
;     ...
; #pragma unroll
;         for (int a = 0; a < 2; ++a)
; #pragma unroll
;             for (int b = 0; b < 2; ++b)
; #pragma unroll
;                 for (int m = 0; m < 4; ++m)
; #pragma unroll
;                     for (int n = 0; n < 2; ++n) acc[a][b][m][n] = (f32x4){0.f, 0.f, 0.f, 0.f};
.LBB0_292:
	s_ashr_i32 s17, s16, 31
	s_lshl_b64 s[18:19], s[16:17], 19
	v_readlane_b32 s20, v253, 45
	v_readlane_b32 s21, v253, 46
	s_add_u32 s18, s20, s18
	s_addc_u32 s19, s21, s19
	s_and_b64 s[20:21], s[0:1], exec
	s_cselect_b32 s17, s19, s25
	s_cselect_b32 s46, s18, s24
	s_ashr_i32 s15, s14, 31
	s_lshl_b64 s[20:21], s[14:15], 19
	s_add_u32 s20, s64, s20
	s_addc_u32 s21, s65, s21
	s_and_b64 s[28:29], s[0:1], exec
	s_cselect_b32 s15, s21, s27
	s_cselect_b32 s47, s20, s26
	s_add_u32 s24, s24, 0x40080
	s_addc_u32 s25, s25, 0
	s_add_u32 s48, s26, 0x100
	v_mov_b32_e32 v0, 0
	s_addc_u32 s49, s27, 0
	s_mov_b32 s50, -2
	ds_read_b128 v[144:147], v151
	ds_read_b128 v[154:157], v151 offset:1024
	ds_read_b128 v[158:161], v151 offset:2048
	ds_read_b128 v[162:165], v151 offset:3072
	ds_read_b128 v[166:169], v152
	ds_read_b128 v[170:173], v152 offset:1024
	ds_read_b128 v[174:177], v152 offset:2048
	ds_read_b128 v[178:181], v152 offset:3072
	s_add_u32 s26, s24, 0xfffc0080
	s_addc_u32 s27, s25, -1
	s_cmp_eq_u32 s50, 12
	s_cselect_b32 s29, s17, s27
	s_cselect_b32 s28, s46, s26
	s_cselect_b32 s27, s15, s49
	s_cselect_b32 s26, s47, s48
	v_lshl_add_u64 v[194:195], s[24:25], 0, v[136:137]
	s_add_i32 m0, s23, 0xc000
	ds_read_b128 v[182:185], v153
	ds_read_b128 v[186:189], v153 offset:1024
	ds_read_b128 v[190:193], v153 offset:2048
	ds_read_b128 v[198:201], v153 offset:3072
	ds_read_b128 v[202:205], v153 offset:4096
	ds_read_b128 v[206:209], v153 offset:5120
	ds_read_b128 v[210:213], v153 offset:6144
	ds_read_b128 v[214:217], v153 offset:7168
	v_mov_b32_e32 v1, v0
	v_mov_b32_e32 v2, v0
	v_mov_b32_e32 v3, v0
	v_mov_b32_e32 v4, v0
	v_mov_b32_e32 v5, v0
	v_mov_b32_e32 v6, v0
	v_mov_b32_e32 v7, v0
	v_mov_b32_e32 v16, v0
	v_mov_b32_e32 v17, v0
	v_mov_b32_e32 v18, v0
	v_mov_b32_e32 v19, v0
	v_mov_b32_e32 v20, v0
	v_mov_b32_e32 v21, v0
	v_mov_b32_e32 v22, v0
	v_mov_b32_e32 v23, v0
	v_mov_b32_e32 v32, v0
	v_mov_b32_e32 v33, v0
	v_mov_b32_e32 v34, v0
	v_mov_b32_e32 v35, v0
	v_mov_b32_e32 v36, v0
	v_mov_b32_e32 v37, v0
	v_mov_b32_e32 v38, v0
	v_mov_b32_e32 v39, v0
	v_mov_b32_e32 v48, v0
	v_mov_b32_e32 v49, v0
	v_mov_b32_e32 v50, v0
	v_mov_b32_e32 v51, v0
	v_mov_b32_e32 v52, v0
	v_mov_b32_e32 v53, v0
	v_mov_b32_e32 v54, v0
	v_mov_b32_e32 v55, v0
	v_mov_b32_e32 v8, v0
	v_mov_b32_e32 v9, v0
	v_mov_b32_e32 v10, v0
	v_mov_b32_e32 v11, v0
	v_mov_b32_e32 v12, v0
	v_mov_b32_e32 v13, v0
	v_mov_b32_e32 v14, v0
	v_mov_b32_e32 v15, v0
	v_mov_b32_e32 v24, v0
	v_mov_b32_e32 v25, v0
	v_mov_b32_e32 v26, v0
	v_mov_b32_e32 v27, v0
	v_mov_b32_e32 v28, v0
	v_mov_b32_e32 v29, v0
	v_mov_b32_e32 v30, v0
	v_mov_b32_e32 v31, v0
	v_mov_b32_e32 v40, v0
	v_mov_b32_e32 v41, v0
	v_mov_b32_e32 v42, v0
	v_mov_b32_e32 v43, v0
	v_mov_b32_e32 v44, v0
	v_mov_b32_e32 v45, v0
	v_mov_b32_e32 v46, v0
	v_mov_b32_e32 v47, v0
	v_mov_b32_e32 v56, v0
	v_mov_b32_e32 v57, v0
	v_mov_b32_e32 v58, v0
	v_mov_b32_e32 v59, v0
	v_mov_b32_e32 v60, v0
	v_mov_b32_e32 v61, v0
	v_mov_b32_e32 v62, v0
	v_mov_b32_e32 v63, v0
	v_mov_b32_e32 v64, v0
	v_mov_b32_e32 v65, v0
	v_mov_b32_e32 v66, v0
	v_mov_b32_e32 v67, v0
	v_mov_b32_e32 v68, v0
	v_mov_b32_e32 v69, v0
	v_mov_b32_e32 v70, v0
	v_mov_b32_e32 v71, v0
	v_mov_b32_e32 v80, v0
	v_mov_b32_e32 v81, v0
	v_mov_b32_e32 v82, v0
	v_mov_b32_e32 v83, v0
	v_mov_b32_e32 v84, v0
	v_mov_b32_e32 v85, v0
	v_mov_b32_e32 v86, v0
	v_mov_b32_e32 v87, v0
	v_mov_b32_e32 v96, v0
	v_mov_b32_e32 v97, v0
	v_mov_b32_e32 v98, v0
	v_mov_b32_e32 v99, v0
	v_mov_b32_e32 v100, v0
	v_mov_b32_e32 v101, v0
	v_mov_b32_e32 v102, v0
	v_mov_b32_e32 v103, v0
	v_mov_b32_e32 v112, v0
	v_mov_b32_e32 v113, v0
	v_mov_b32_e32 v114, v0
	v_mov_b32_e32 v115, v0
	v_mov_b32_e32 v116, v0
	v_mov_b32_e32 v117, v0
	v_mov_b32_e32 v118, v0
	v_mov_b32_e32 v119, v0
	v_mov_b32_e32 v72, v0
	v_mov_b32_e32 v73, v0
	v_mov_b32_e32 v74, v0
	v_mov_b32_e32 v75, v0
	v_mov_b32_e32 v76, v0
	v_mov_b32_e32 v77, v0
	v_mov_b32_e32 v78, v0
	v_mov_b32_e32 v79, v0
	v_mov_b32_e32 v88, v0
	v_mov_b32_e32 v89, v0
	v_mov_b32_e32 v90, v0
	v_mov_b32_e32 v91, v0
	v_mov_b32_e32 v92, v0
	v_mov_b32_e32 v93, v0
	v_mov_b32_e32 v94, v0
	v_mov_b32_e32 v95, v0
	v_mov_b32_e32 v104, v0
	v_mov_b32_e32 v105, v0
	v_mov_b32_e32 v106, v0
	v_mov_b32_e32 v107, v0
	v_mov_b32_e32 v108, v0
	v_mov_b32_e32 v109, v0
	v_mov_b32_e32 v110, v0
	v_mov_b32_e32 v111, v0
	v_mov_b32_e32 v120, v0
	v_mov_b32_e32 v121, v0
	v_mov_b32_e32 v122, v0
	v_mov_b32_e32 v123, v0
	v_mov_b32_e32 v124, v0
	v_mov_b32_e32 v125, v0
	v_mov_b32_e32 v126, v0
	v_mov_b32_e32 v127, v0
	s_cmp_eq_u32 s37, 1
	s_cselect_b32 s101, 0x7fffffff, -2
	s_branch .Lzh0_mid

; #define PG8_STAGE(bufoff, gbase, voff) do { _Pragma("unroll") for (int _i = 0; _i < 2; ++_i) \
;         __builtin_amdgcn_global_load_lds((const unsigned*)((const char*)(gbase) + (voff)[_i]), (PG8_LAS unsigned*)(lds + (bufoff) + ldsw + _i * 8192), 16, 0, 0); } while (0)
; #define PG8_LDA(dst, b, h) do { _Pragma("unroll") for (int m = 0; m < 4; ++m) _Pragma("unroll") for (int k = 0; k < 2; ++k) dst[m][k] = *(const PG8_LAS bf16x8*)(lds + PG8_SA(b, h) + aoff + m * 2048 + k * 1024); } while (0)
; #define PG8_LDB(dst, b, h) do { _Pragma("unroll") for (int n = 0; n < 2; ++n) _Pragma("unroll") for (int k = 0; k < 2; ++k) dst[n][k] = *(const PG8_LAS bf16x8*)(lds + PG8_SB(b, h) + boff + n * 2048 + k * 1024); } while (0)
; #define PG8_MMA(ai, bj, At, Bt) do { __builtin_amdgcn_s_setprio(1); _Pragma("unroll") for (int m = 0; m < 4; ++m) _Pragma("unroll") for (int n = 0; n < 2; ++n) _Pragma("unroll") for (int k = 0; k < 2; ++k) \
;         acc[ai][bj][m][n] = __builtin_amdgcn_mfma_f32_16x16x32_bf16(Bt[n][k], At[m][k], acc[ai][bj][m][n], 0, 0, 0); __builtin_amdgcn_s_setprio(0); } while (0)
; #define PG8_WAIT_V(n) asm volatile("s_waitcnt vmcnt(" #n ")" ::: "memory")
; #define PG8_WAIT_L(n) asm volatile("s_waitcnt lgkmcnt(" #n ")" ::: "memory")
; #define PG8_BAR __builtin_amdgcn_s_barrier()
; #define PG8_SCHED __builtin_amdgcn_sched_barrier(0)
; template <class Epi, class Sched, bool ALIGN_EPI = false, bool SP2 = false>
; __device__ __forceinline__ void gemm_phase(PG8_LAS unsigned char* lds, const Gemm g, const Sched& S, const Epi& E) {
;     ...
;             PG8_LDB(B0, 0, 0); PG8_LDB(B1, 0, 1); PG8_SCHED; PG8_LDA(At, 0, 0); PG8_STAGE(PG8_SA(1, 1), a1 + hstep, voffA);
;             PG8_WAIT_V(8); PG8_WAIT_L(0); PG8_BAR; PG8_MMA(0, 0, At, B0); PG8_MMA(0, 1, At, B1); PG8_BAR; PG8_SCHED;
.Lzh0_mid:
	global_load_lds_dwordx4 v[194:195], off
	v_lshl_add_u64 v[194:195], s[24:25], 0, v[138:139]
	s_add_i32 m0, s23, 0xe000
	s_nop 0
	global_load_lds_dwordx4 v[194:195], off
	s_cmp_eq_u32 s50, s101
	s_cbranch_scc1 .Lrw0_r0
	s_waitcnt vmcnt(8)

; #define PG8_STAGE(bufoff, gbase, voff) do { _Pragma("unroll") for (int _i = 0; _i < 2; ++_i) \
;         __builtin_amdgcn_global_load_lds((const unsigned*)((const char*)(gbase) + (voff)[_i]), (PG8_LAS unsigned*)(lds + (bufoff) + ldsw + _i * 8192), 16, 0, 0); } while (0)
; #define PG8_LDA(dst, b, h) do { _Pragma("unroll") for (int m = 0; m < 4; ++m) _Pragma("unroll") for (int k = 0; k < 2; ++k) dst[m][k] = *(const PG8_LAS bf16x8*)(lds + PG8_SA(b, h) + aoff + m * 2048 + k * 1024); } while (0)
; #define PG8_LDB(dst, b, h) do { _Pragma("unroll") for (int n = 0; n < 2; ++n) _Pragma("unroll") for (int k = 0; k < 2; ++k) dst[n][k] = *(const PG8_LAS bf16x8*)(lds + PG8_SB(b, h) + boff + n * 2048 + k * 1024); } while (0)
; #define PG8_SCHED __builtin_amdgcn_sched_barrier(0)
; template <class Epi, class Sched, bool ALIGN_EPI = false, bool SP2 = false>
; __device__ __forceinline__ void gemm_phase(PG8_LAS unsigned char* lds, const Gemm g, const Sched& S, const Epi& E) {
;     ...
;         const bool has_next = S.next(ui + 1, nxt);
;         const char* nA = has_next ? (const char*)g.A + (size_t)nxt.pm * tstep : cA; const char* nB = has_next ? (const char*)g.Bt + (size_t)nxt.pn * tstep : cB;
;         for (int t = 0; t < nt; t += 2) {
;             const bool last = (t == nt - 2);
;             const char* a1 = cA + (size_t)(t + 1) * kstep;
;             const char* a2 = last ? nA : cA + (size_t)(t + 2) * kstep; const char* b2 = last ? nB : cB + (size_t)(t + 2) * kstep;
;             const char* a3 = a2 + kstep; const char* b3 = b2 + kstep;
;             if (last && has_next) S.a_ready(nxt);
;             if constexpr (SP2) {
;             PG8_LDB(B0, 0, 0); PG8_LDB(B1, 0, 1); PG8_SCHED; PG8_LDA(At, 0, 0); PG8_STAGE(PG8_SA(1, 1), a1 + hstep, voffA);
;     ...
; #pragma unroll
;         for (int a = 0; a < 2; ++a)
; #pragma unroll
;             for (int b = 0; b < 2; ++b)
; #pragma unroll
;                 for (int m = 0; m < 4; ++m)
; #pragma unroll
;                     for (int n = 0; n < 2; ++n) acc[a][b][m][n] = (f32x4){0.f, 0.f, 0.f, 0.f};
.LBB0_369:
	s_add_u32 s22, s22, 0xb0080
	s_addc_u32 s23, s23, 0
	s_add_u32 s46, s24, 0x100
	v_mov_b32_e32 v0, 0
	s_addc_u32 s47, s25, 0
	s_mov_b32 s48, -2
	v_mov_b32_e32 v1, v0
	v_mov_b32_e32 v2, v0
	v_mov_b32_e32 v3, v0
	v_mov_b32_e32 v4, v0
	s_waitcnt lgkmcnt(0)
	ds_read_b128 v[144:147], v151
	ds_read_b128 v[156:159], v151 offset:1024
	ds_read_b128 v[160:163], v151 offset:2048
	ds_read_b128 v[164:167], v151 offset:3072
	ds_read_b128 v[168:171], v152
	ds_read_b128 v[172:175], v152 offset:1024
	ds_read_b128 v[176:179], v152 offset:2048
	ds_read_b128 v[180:183], v152 offset:3072
	s_add_u32 s24, s22, 0xfff50080
	s_addc_u32 s25, s23, -1
	s_cmp_eq_u32 s48, 40
	s_cselect_b32 s27, s5, s25
	s_cselect_b32 s26, s4, s24
	s_cselect_b32 s25, s21, s47
	s_cselect_b32 s24, s20, s46
	v_lshl_add_u64 v[218:219], s[22:23], 0, v[136:137]
	s_add_i32 m0, s29, 0xc000
	ds_read_b128 v[184:187], v153
	ds_read_b128 v[188:191], v153 offset:1024
	ds_read_b128 v[192:195], v153 offset:2048
	ds_read_b128 v[198:201], v153 offset:3072
	ds_read_b128 v[202:205], v153 offset:4096
	ds_read_b128 v[206:209], v153 offset:5120
	ds_read_b128 v[210:213], v153 offset:6144
	ds_read_b128 v[214:217], v153 offset:7168
	v_mov_b32_e32 v5, v0
	v_mov_b32_e32 v6, v0
	v_mov_b32_e32 v7, v0
	v_mov_b32_e32 v16, v0
	v_mov_b32_e32 v17, v0
	v_mov_b32_e32 v18, v0
	v_mov_b32_e32 v19, v0
	v_mov_b32_e32 v20, v0
	v_mov_b32_e32 v21, v0
	v_mov_b32_e32 v22, v0
	v_mov_b32_e32 v23, v0
	v_mov_b32_e32 v32, v0
	v_mov_b32_e32 v33, v0
	v_mov_b32_e32 v34, v0
	v_mov_b32_e32 v35, v0
	v_mov_b32_e32 v36, v0
	v_mov_b32_e32 v37, v0
	v_mov_b32_e32 v38, v0
	v_mov_b32_e32 v39, v0
	v_mov_b32_e32 v48, v0
	v_mov_b32_e32 v49, v0
	v_mov_b32_e32 v50, v0
	v_mov_b32_e32 v51, v0
	v_mov_b32_e32 v52, v0
	v_mov_b32_e32 v53, v0
	v_mov_b32_e32 v54, v0
	v_mov_b32_e32 v55, v0
	v_mov_b32_e32 v8, v0
	v_mov_b32_e32 v9, v0
	v_mov_b32_e32 v10, v0
	v_mov_b32_e32 v11, v0
	v_mov_b32_e32 v12, v0
	v_mov_b32_e32 v13, v0
	v_mov_b32_e32 v14, v0
	v_mov_b32_e32 v15, v0
	v_mov_b32_e32 v24, v0
	v_mov_b32_e32 v25, v0
	v_mov_b32_e32 v26, v0
	v_mov_b32_e32 v27, v0
	v_mov_b32_e32 v28, v0
	v_mov_b32_e32 v29, v0
	v_mov_b32_e32 v30, v0
	v_mov_b32_e32 v31, v0
	v_mov_b32_e32 v40, v0
	v_mov_b32_e32 v41, v0
	v_mov_b32_e32 v42, v0
	v_mov_b32_e32 v43, v0
	v_mov_b32_e32 v44, v0
	v_mov_b32_e32 v45, v0
	v_mov_b32_e32 v46, v0
	v_mov_b32_e32 v47, v0
	v_mov_b32_e32 v56, v0
	v_mov_b32_e32 v57, v0
	v_mov_b32_e32 v58, v0
	v_mov_b32_e32 v59, v0
	v_mov_b32_e32 v60, v0
	v_mov_b32_e32 v61, v0
	v_mov_b32_e32 v62, v0
	v_mov_b32_e32 v63, v0
	v_mov_b32_e32 v64, v0
	v_mov_b32_e32 v65, v0
	v_mov_b32_e32 v66, v0
	v_mov_b32_e32 v67, v0
	v_mov_b32_e32 v68, v0
	v_mov_b32_e32 v69, v0
	v_mov_b32_e32 v70, v0
	v_mov_b32_e32 v71, v0
	v_mov_b32_e32 v80, v0
	v_mov_b32_e32 v81, v0
	v_mov_b32_e32 v82, v0
	v_mov_b32_e32 v83, v0
	v_mov_b32_e32 v84, v0
	v_mov_b32_e32 v85, v0
	v_mov_b32_e32 v86, v0
	v_mov_b32_e32 v87, v0
	v_mov_b32_e32 v96, v0
	v_mov_b32_e32 v97, v0
	v_mov_b32_e32 v98, v0
	v_mov_b32_e32 v99, v0
	v_mov_b32_e32 v100, v0
	v_mov_b32_e32 v101, v0
	v_mov_b32_e32 v102, v0
	v_mov_b32_e32 v103, v0
	v_mov_b32_e32 v112, v0
	v_mov_b32_e32 v113, v0
	v_mov_b32_e32 v114, v0
	v_mov_b32_e32 v115, v0
	v_mov_b32_e32 v116, v0
	v_mov_b32_e32 v117, v0
	v_mov_b32_e32 v118, v0
	v_mov_b32_e32 v119, v0
	v_mov_b32_e32 v72, v0
	v_mov_b32_e32 v73, v0
	v_mov_b32_e32 v74, v0
	v_mov_b32_e32 v75, v0
	v_mov_b32_e32 v76, v0
	v_mov_b32_e32 v77, v0
	v_mov_b32_e32 v78, v0
	v_mov_b32_e32 v79, v0
	v_mov_b32_e32 v88, v0
	v_mov_b32_e32 v89, v0
	v_mov_b32_e32 v90, v0
	v_mov_b32_e32 v91, v0
	v_mov_b32_e32 v92, v0
	v_mov_b32_e32 v93, v0
	v_mov_b32_e32 v94, v0
	v_mov_b32_e32 v95, v0
	v_mov_b32_e32 v104, v0
	v_mov_b32_e32 v105, v0
	v_mov_b32_e32 v106, v0
	v_mov_b32_e32 v107, v0
	v_mov_b32_e32 v108, v0
	v_mov_b32_e32 v109, v0
	v_mov_b32_e32 v110, v0
	v_mov_b32_e32 v111, v0
	v_mov_b32_e32 v120, v0
	v_mov_b32_e32 v121, v0
	v_mov_b32_e32 v122, v0
	v_mov_b32_e32 v123, v0
	v_mov_b32_e32 v124, v0
	v_mov_b32_e32 v125, v0
	v_mov_b32_e32 v126, v0
	v_mov_b32_e32 v127, v0
	s_branch .Lzh1_mid

; #define PG8_STAGE(bufoff, gbase, voff) do { _Pragma("unroll") for (int _i = 0; _i < 2; ++_i) \
;         __builtin_amdgcn_global_load_lds((const unsigned*)((const char*)(gbase) + (voff)[_i]), (PG8_LAS unsigned*)(lds + (bufoff) + ldsw + _i * 8192), 16, 0, 0); } while (0)
; #define PG8_LDA(dst, b, h) do { _Pragma("unroll") for (int m = 0; m < 4; ++m) _Pragma("unroll") for (int k = 0; k < 2; ++k) dst[m][k] = *(const PG8_LAS bf16x8*)(lds + PG8_SA(b, h) + aoff + m * 2048 + k * 1024); } while (0)
; #define PG8_LDB(dst, b, h) do { _Pragma("unroll") for (int n = 0; n < 2; ++n) _Pragma("unroll") for (int k = 0; k < 2; ++k) dst[n][k] = *(const PG8_LAS bf16x8*)(lds + PG8_SB(b, h) + boff + n * 2048 + k * 1024); } while (0)
; #define PG8_MMA(ai, bj, At, Bt) do { __builtin_amdgcn_s_setprio(1); _Pragma("unroll") for (int m = 0; m < 4; ++m) _Pragma("unroll") for (int n = 0; n < 2; ++n) _Pragma("unroll") for (int k = 0; k < 2; ++k) \
;         acc[ai][bj][m][n] = __builtin_amdgcn_mfma_f32_16x16x32_bf16(Bt[n][k], At[m][k], acc[ai][bj][m][n], 0, 0, 0); __builtin_amdgcn_s_setprio(0); } while (0)
; #define PG8_WAIT_V(n) asm volatile("s_waitcnt vmcnt(" #n ")" ::: "memory")
; #define PG8_WAIT_L(n) asm volatile("s_waitcnt lgkmcnt(" #n ")" ::: "memory")
; #define PG8_BAR __builtin_amdgcn_s_barrier()
; #define PG8_SCHED __builtin_amdgcn_sched_barrier(0)
; template <class Epi, class Sched, bool ALIGN_EPI = false, bool SP2 = false>
; __device__ __forceinline__ void gemm_phase(PG8_LAS unsigned char* lds, const Gemm g, const Sched& S, const Epi& E) {
;     ...
;             PG8_LDB(B0, 0, 0); PG8_LDB(B1, 0, 1); PG8_SCHED; PG8_LDA(At, 0, 0); PG8_STAGE(PG8_SA(1, 1), a1 + hstep, voffA);
;             PG8_WAIT_V(8); PG8_WAIT_L(0); PG8_BAR; PG8_MMA(0, 0, At, B0); PG8_MMA(0, 1, At, B1); PG8_BAR; PG8_SCHED;
;             PG8_LDA(At, 0, 1); PG8_STAGE(PG8_SB(0, 0), b2, voffB); PG8_STAGE(PG8_SB(0, 1), b2 + hstep, voffB); PG8_STAGE(PG8_SA(0, 0), a2, voffA);
;             PG8_WAIT_V(8); PG8_WAIT_L(0); PG8_BAR; PG8_MMA(1, 0, At, B0); PG8_MMA(1, 1, At, B1); PG8_BAR; PG8_SCHED;
.Lzh1_mid:
	global_load_lds_dwordx4 v[218:219], off
	v_lshl_add_u64 v[218:219], s[22:23], 0, v[138:139]
	s_add_i32 m0, s29, 0xe000
	s_nop 0
	global_load_lds_dwordx4 v[218:219], off
	s_waitcnt vmcnt(8)
	s_waitcnt lgkmcnt(0)
	s_barrier
	s_setprio 1
	s_waitcnt lgkmcnt(0)
	v_mfma_f32_16x16x32_bf16 v[124:127], v[144:147], v[184:187], v[124:127]
	v_mfma_f32_16x16x32_bf16 v[120:123], v[160:163], v[184:187], v[120:123]
	v_mfma_f32_16x16x32_bf16 v[108:111], v[144:147], v[192:195], v[108:111]
	v_mfma_f32_16x16x32_bf16 v[104:107], v[160:163], v[192:195], v[104:107]
	v_mfma_f32_16x16x32_bf16 v[92:95], v[144:147], v[202:205], v[92:95]
	v_mfma_f32_16x16x32_bf16 v[88:91], v[160:163], v[202:205], v[88:91]
	v_mfma_f32_16x16x32_bf16 v[76:79], v[144:147], v[210:213], v[76:79]
	v_mfma_f32_16x16x32_bf16 v[72:75], v[160:163], v[210:213], v[72:75]
	v_mfma_f32_16x16x32_bf16 v[124:127], v[156:159], v[188:191], v[124:127]
	v_mfma_f32_16x16x32_bf16 v[120:123], v[164:167], v[188:191], v[120:123]
	v_mfma_f32_16x16x32_bf16 v[108:111], v[156:159], v[198:201], v[108:111]
	v_mfma_f32_16x16x32_bf16 v[104:107], v[164:167], v[198:201], v[104:107]
	v_mfma_f32_16x16x32_bf16 v[92:95], v[156:159], v[206:209], v[92:95]
	v_mfma_f32_16x16x32_bf16 v[88:91], v[164:167], v[206:209], v[88:91]
	v_mfma_f32_16x16x32_bf16 v[76:79], v[156:159], v[214:217], v[76:79]
	v_mfma_f32_16x16x32_bf16 v[72:75], v[164:167], v[214:217], v[72:75]
	s_setprio 0
	s_setprio 1
	v_mfma_f32_16x16x32_bf16 v[116:119], v[168:171], v[184:187], v[116:119]
	v_mfma_f32_16x16x32_bf16 v[112:115], v[176:179], v[184:187], v[112:115]
	v_mfma_f32_16x16x32_bf16 v[100:103], v[168:171], v[192:195], v[100:103]
	v_mfma_f32_16x16x32_bf16 v[96:99], v[176:179], v[192:195], v[96:99]
	v_mfma_f32_16x16x32_bf16 v[84:87], v[168:171], v[202:205], v[84:87]
	v_mfma_f32_16x16x32_bf16 v[80:83], v[176:179], v[202:205], v[80:83]
	v_mfma_f32_16x16x32_bf16 v[68:71], v[168:171], v[210:213], v[68:71]
	v_mfma_f32_16x16x32_bf16 v[64:67], v[176:179], v[210:213], v[64:67]
	v_mfma_f32_16x16x32_bf16 v[116:119], v[172:175], v[188:191], v[116:119]
	v_mfma_f32_16x16x32_bf16 v[112:115], v[180:183], v[188:191], v[112:115]
	v_mfma_f32_16x16x32_bf16 v[100:103], v[172:175], v[198:201], v[100:103]
	v_mfma_f32_16x16x32_bf16 v[96:99], v[180:183], v[198:201], v[96:99]
	v_mfma_f32_16x16x32_bf16 v[84:87], v[172:175], v[206:209], v[84:87]
	v_mfma_f32_16x16x32_bf16 v[80:83], v[180:183], v[206:209], v[80:83]
	v_mfma_f32_16x16x32_bf16 v[68:71], v[172:175], v[214:217], v[68:71]
	v_mfma_f32_16x16x32_bf16 v[64:67], v[180:183], v[214:217], v[64:67]
	s_setprio 0
	s_barrier
	s_add_i32 s49, s40, s28
	v_lshl_add_u64 v[218:219], s[24:25], 0, v[130:131]
	s_mov_b32 m0, s49
	ds_read_b128 v[184:187], v153 offset:16384
	ds_read_b128 v[188:191], v153 offset:17408
	ds_read_b128 v[192:195], v153 offset:18432
	ds_read_b128 v[198:201], v153 offset:19456
	ds_read_b128 v[202:205], v153 offset:20480
	ds_read_b128 v[206:209], v153 offset:21504
	ds_read_b128 v[210:213], v153 offset:22528
	ds_read_b128 v[214:217], v153 offset:23552
	global_load_lds_dwordx4 v[218:219], off
	s_add_i32 m0, s49, 0x2000
	s_add_u32 s50, s24, 0xb0000
	v_lshl_add_u64 v[220:221], s[24:25], 0, v[134:135]
	s_addc_u32 s51, s25, 0
	s_add_i32 s49, s41, s28
	global_load_lds_dwordx4 v[220:221], off
	v_lshl_add_u64 v[222:223], s[50:51], 0, v[130:131]
	s_mov_b32 m0, s49
	v_lshl_add_u64 v[224:225], s[26:27], 0, v[132:133]
	global_load_lds_dwordx4 v[222:223], off
	v_lshl_add_u64 v[222:223], s[50:51], 0, v[134:135]
	s_add_i32 m0, s49, 0x2000
	s_nop 0
	global_load_lds_dwordx4 v[222:223], off
	v_lshl_add_u64 v[222:223], s[26:27], 0, v[128:129]
	s_mov_b32 m0, s29
	s_nop 0
	global_load_lds_dwordx4 v[222:223], off
	s_mov_b32 m0, s30
	s_nop 0
	global_load_lds_dwordx4 v[224:225], off
	s_waitcnt vmcnt(8)
	s_waitcnt lgkmcnt(0)
	s_barrier
	s_setprio 1
	s_waitcnt lgkmcnt(0)
	v_mfma_f32_16x16x32_bf16 v[60:63], v[144:147], v[184:187], v[60:63]
	v_mfma_f32_16x16x32_bf16 v[56:59], v[160:163], v[184:187], v[56:59]
	v_mfma_f32_16x16x32_bf16 v[44:47], v[144:147], v[192:195], v[44:47]
	v_mfma_f32_16x16x32_bf16 v[40:43], v[160:163], v[192:195], v[40:43]
	v_mfma_f32_16x16x32_bf16 v[28:31], v[144:147], v[202:205], v[28:31]
	v_mfma_f32_16x16x32_bf16 v[24:27], v[160:163], v[202:205], v[24:27]
	v_mfma_f32_16x16x32_bf16 v[12:15], v[144:147], v[210:213], v[12:15]
	v_mfma_f32_16x16x32_bf16 v[8:11], v[160:163], v[210:213], v[8:11]
	v_mfma_f32_16x16x32_bf16 v[60:63], v[156:159], v[188:191], v[60:63]
	v_mfma_f32_16x16x32_bf16 v[56:59], v[164:167], v[188:191], v[56:59]
	v_mfma_f32_16x16x32_bf16 v[44:47], v[156:159], v[198:201], v[44:47]
	v_mfma_f32_16x16x32_bf16 v[40:43], v[164:167], v[198:201], v[40:43]
	v_mfma_f32_16x16x32_bf16 v[28:31], v[156:159], v[206:209], v[28:31]
	v_mfma_f32_16x16x32_bf16 v[24:27], v[164:167], v[206:209], v[24:27]
	v_mfma_f32_16x16x32_bf16 v[12:15], v[156:159], v[214:217], v[12:15]
	v_mfma_f32_16x16x32_bf16 v[8:11], v[164:167], v[214:217], v[8:11]
	s_setprio 0
	s_setprio 1
	v_mfma_f32_16x16x32_bf16 v[52:55], v[168:171], v[184:187], v[52:55]
	v_mfma_f32_16x16x32_bf16 v[48:51], v[176:179], v[184:187], v[48:51]
	v_mfma_f32_16x16x32_bf16 v[36:39], v[168:171], v[192:195], v[36:39]
	v_mfma_f32_16x16x32_bf16 v[32:35], v[176:179], v[192:195], v[32:35]
	v_mfma_f32_16x16x32_bf16 v[20:23], v[168:171], v[202:205], v[20:23]
	v_mfma_f32_16x16x32_bf16 v[16:19], v[176:179], v[202:205], v[16:19]
	v_mfma_f32_16x16x32_bf16 v[4:7], v[168:171], v[210:213], v[4:7]
	v_mfma_f32_16x16x32_bf16 v[0:3], v[176:179], v[210:213], v[0:3]
	v_mfma_f32_16x16x32_bf16 v[52:55], v[172:175], v[188:191], v[52:55]
	v_mfma_f32_16x16x32_bf16 v[48:51], v[180:183], v[188:191], v[48:51]
	v_mfma_f32_16x16x32_bf16 v[36:39], v[172:175], v[198:201], v[36:39]
	v_mfma_f32_16x16x32_bf16 v[32:35], v[180:183], v[198:201], v[32:35]
	v_mfma_f32_16x16x32_bf16 v[20:23], v[172:175], v[206:209], v[20:23]
	v_mfma_f32_16x16x32_bf16 v[16:19], v[180:183], v[206:209], v[16:19]
	v_mfma_f32_16x16x32_bf16 v[4:7], v[172:175], v[214:217], v[4:7]
	v_mfma_f32_16x16x32_bf16 v[0:3], v[180:183], v[214:217], v[0:3]
	s_setprio 0
	s_barrier
; #define PG8_STAGE(bufoff, gbase, voff) do { _Pragma("unroll") for (int _i = 0; _i < 2; ++_i) \
;         __builtin_amdgcn_global_load_lds((const unsigned*)((const char*)(gbase) + (voff)[_i]), (PG8_LAS unsigned*)(lds + (bufoff) + ldsw + _i * 8192), 16, 0, 0); } while (0)
; #define PG8_LDA(dst, b, h) do { _Pragma("unroll") for (int m = 0; m < 4; ++m) _Pragma("unroll") for (int k = 0; k < 2; ++k) dst[m][k] = *(const PG8_LAS bf16x8*)(lds + PG8_SA(b, h) + aoff + m * 2048 + k * 1024); } while (0)
; #define PG8_LDB(dst, b, h) do { _Pragma("unroll") for (int n = 0; n < 2; ++n) _Pragma("unroll") for (int k = 0; k < 2; ++k) dst[n][k] = *(const PG8_LAS bf16x8*)(lds + PG8_SB(b, h) + boff + n * 2048 + k * 1024); } while (0)
; #define PG8_MMA(ai, bj, At, Bt) do { __builtin_amdgcn_s_setprio(1); _Pragma("unroll") for (int m = 0; m < 4; ++m) _Pragma("unroll") for (int n = 0; n < 2; ++n) _Pragma("unroll") for (int k = 0; k < 2; ++k) \
;         acc[ai][bj][m][n] = __builtin_amdgcn_mfma_f32_16x16x32_bf16(Bt[n][k], At[m][k], acc[ai][bj][m][n], 0, 0, 0); __builtin_amdgcn_s_setprio(0); } while (0)
; #define PG8_WAIT_V(n) asm volatile("s_waitcnt vmcnt(" #n ")" ::: "memory")
; #define PG8_WAIT_L(n) asm volatile("s_waitcnt lgkmcnt(" #n ")" ::: "memory")
; #define PG8_BAR __builtin_amdgcn_s_barrier()
; #define PG8_SCHED __builtin_amdgcn_sched_barrier(0)
; template <class Epi, class Sched, bool ALIGN_EPI = false, bool SP2 = false>
; __device__ __forceinline__ void gemm_phase(PG8_LAS unsigned char* lds, const Gemm g, const Sched& S, const Epi& E) {
;     ...
;             PG8_LDB(B0, 1, 0); PG8_LDB(B1, 1, 1); PG8_SCHED; PG8_LDA(At, 1, 0); PG8_STAGE(PG8_SA(0, 1), a2 + hstep, voffA);
;             PG8_WAIT_V(8); PG8_WAIT_L(0); PG8_BAR; PG8_MMA(0, 0, At, B0); PG8_MMA(0, 1, At, B1); PG8_BAR; PG8_SCHED;
	s_add_i32 s49, 0, 0x18000
	v_add_u32_e32 v155, s49, v149
	s_add_i32 s50, 0, 0x1c000
	ds_read_b128 v[144:147], v155
	ds_read_b128 v[156:159], v155 offset:1024
	ds_read_b128 v[160:163], v155 offset:2048
	ds_read_b128 v[164:167], v155 offset:3072
	v_add_u32_e32 v155, s50, v149
	ds_read_b128 v[168:171], v155
	ds_read_b128 v[172:175], v155 offset:1024
	ds_read_b128 v[176:179], v155 offset:2048
	ds_read_b128 v[180:183], v155 offset:3072
	s_add_u32 s26, s26, 0xb0000
	s_addc_u32 s27, s27, 0
	s_mov_b32 m0, s31
	v_lshl_add_u64 v[226:227], s[26:27], 0, v[128:129]
	ds_read_b128 v[184:187], v153 offset:32768
	ds_read_b128 v[188:191], v153 offset:33792
	ds_read_b128 v[192:195], v153 offset:34816
	ds_read_b128 v[198:201], v153 offset:35840
	ds_read_b128 v[202:205], v153 offset:36864
	ds_read_b128 v[206:209], v153 offset:37888
	ds_read_b128 v[210:213], v153 offset:38912
	ds_read_b128 v[214:217], v153 offset:39936
	global_load_lds_dwordx4 v[226:227], off
	v_lshl_add_u64 v[226:227], s[26:27], 0, v[132:133]
	s_mov_b32 m0, s33
	s_nop 0
	global_load_lds_dwordx4 v[226:227], off
	s_waitcnt vmcnt(8)
	s_waitcnt lgkmcnt(0)
	s_barrier
	s_setprio 1
	s_waitcnt lgkmcnt(0)
	v_mfma_f32_16x16x32_bf16 v[124:127], v[144:147], v[184:187], v[124:127]
	v_mfma_f32_16x16x32_bf16 v[120:123], v[160:163], v[184:187], v[120:123]
	v_mfma_f32_16x16x32_bf16 v[108:111], v[144:147], v[192:195], v[108:111]
	v_mfma_f32_16x16x32_bf16 v[104:107], v[160:163], v[192:195], v[104:107]
	v_mfma_f32_16x16x32_bf16 v[92:95], v[144:147], v[202:205], v[92:95]
	v_mfma_f32_16x16x32_bf16 v[88:91], v[160:163], v[202:205], v[88:91]
	v_mfma_f32_16x16x32_bf16 v[76:79], v[144:147], v[210:213], v[76:79]
	v_mfma_f32_16x16x32_bf16 v[72:75], v[160:163], v[210:213], v[72:75]
	v_mfma_f32_16x16x32_bf16 v[124:127], v[156:159], v[188:191], v[124:127]
	v_mfma_f32_16x16x32_bf16 v[120:123], v[164:167], v[188:191], v[120:123]
	v_mfma_f32_16x16x32_bf16 v[108:111], v[156:159], v[198:201], v[108:111]
	v_mfma_f32_16x16x32_bf16 v[104:107], v[164:167], v[198:201], v[104:107]
	v_mfma_f32_16x16x32_bf16 v[92:95], v[156:159], v[206:209], v[92:95]
	v_mfma_f32_16x16x32_bf16 v[88:91], v[164:167], v[206:209], v[88:91]
	v_mfma_f32_16x16x32_bf16 v[76:79], v[156:159], v[214:217], v[76:79]
	v_mfma_f32_16x16x32_bf16 v[72:75], v[164:167], v[214:217], v[72:75]
	s_setprio 0
	s_setprio 1
	v_mfma_f32_16x16x32_bf16 v[116:119], v[168:171], v[184:187], v[116:119]
	v_mfma_f32_16x16x32_bf16 v[112:115], v[176:179], v[184:187], v[112:115]
	v_mfma_f32_16x16x32_bf16 v[100:103], v[168:171], v[192:195], v[100:103]
	v_mfma_f32_16x16x32_bf16 v[96:99], v[176:179], v[192:195], v[96:99]
	v_mfma_f32_16x16x32_bf16 v[84:87], v[168:171], v[202:205], v[84:87]
	v_mfma_f32_16x16x32_bf16 v[80:83], v[176:179], v[202:205], v[80:83]
	v_mfma_f32_16x16x32_bf16 v[68:71], v[168:171], v[210:213], v[68:71]
	v_mfma_f32_16x16x32_bf16 v[64:67], v[176:179], v[210:213], v[64:67]
	v_mfma_f32_16x16x32_bf16 v[116:119], v[172:175], v[188:191], v[116:119]
	v_mfma_f32_16x16x32_bf16 v[112:115], v[180:183], v[188:191], v[112:115]
	v_mfma_f32_16x16x32_bf16 v[100:103], v[172:175], v[198:201], v[100:103]
	v_mfma_f32_16x16x32_bf16 v[96:99], v[180:183], v[198:201], v[96:99]
	v_mfma_f32_16x16x32_bf16 v[84:87], v[172:175], v[206:209], v[84:87]
	v_mfma_f32_16x16x32_bf16 v[80:83], v[180:183], v[206:209], v[80:83]
	v_mfma_f32_16x16x32_bf16 v[68:71], v[172:175], v[214:217], v[68:71]
	v_mfma_f32_16x16x32_bf16 v[64:67], v[180:183], v[214:217], v[64:67]
	s_setprio 0
	s_barrier
; #define PG8_STAGE(bufoff, gbase, voff) do { _Pragma("unroll") for (int _i = 0; _i < 2; ++_i) \
;         __builtin_amdgcn_global_load_lds((const unsigned*)((const char*)(gbase) + (voff)[_i]), (PG8_LAS unsigned*)(lds + (bufoff) + ldsw + _i * 8192), 16, 0, 0); } while (0)
; #define PG8_LDA(dst, b, h) do { _Pragma("unroll") for (int m = 0; m < 4; ++m) _Pragma("unroll") for (int k = 0; k < 2; ++k) dst[m][k] = *(const PG8_LAS bf16x8*)(lds + PG8_SA(b, h) + aoff + m * 2048 + k * 1024); } while (0)
; #define PG8_MMA(ai, bj, At, Bt) do { __builtin_amdgcn_s_setprio(1); _Pragma("unroll") for (int m = 0; m < 4; ++m) _Pragma("unroll") for (int n = 0; n < 2; ++n) _Pragma("unroll") for (int k = 0; k < 2; ++k) \
;         acc[ai][bj][m][n] = __builtin_amdgcn_mfma_f32_16x16x32_bf16(Bt[n][k], At[m][k], acc[ai][bj][m][n], 0, 0, 0); __builtin_amdgcn_s_setprio(0); } while (0)
; #define PG8_WAIT_V(n) asm volatile("s_waitcnt vmcnt(" #n ")" ::: "memory")
; #define PG8_WAIT_L(n) asm volatile("s_waitcnt lgkmcnt(" #n ")" ::: "memory")
; #define PG8_BAR __builtin_amdgcn_s_barrier()
; #define PG8_SCHED __builtin_amdgcn_sched_barrier(0)
; template <class Epi, class Sched, bool ALIGN_EPI = false, bool SP2 = false>
; __device__ __forceinline__ void gemm_phase(PG8_LAS unsigned char* lds, const Gemm g, const Sched& S, const Epi& E) {
;     ...
;             PG8_LDA(At, 1, 1); PG8_STAGE(PG8_SB(1, 0), b3, voffB); PG8_STAGE(PG8_SB(1, 1), b3 + hstep, voffB); PG8_STAGE(PG8_SA(1, 0), a3, voffA);
;             PG8_WAIT_V(8); PG8_WAIT_L(0); PG8_BAR; PG8_MMA(1, 0, At, B0); PG8_MMA(1, 1, At, B1); PG8_BAR; PG8_SCHED;
;     ...
;         if constexpr (ALIGN_EPI) { if (wr == 0) PG8_BAR; }
	s_add_i32 s26, s49, s28
	v_lshl_add_u64 v[218:219], v[218:219], 0, s[16:17]
	s_mov_b32 m0, s26
	ds_read_b128 v[184:187], v153 offset:49152
	ds_read_b128 v[188:191], v153 offset:50176
	ds_read_b128 v[192:195], v153 offset:51200
	ds_read_b128 v[198:201], v153 offset:52224
	ds_read_b128 v[202:205], v153 offset:53248
	ds_read_b128 v[206:209], v153 offset:54272
	ds_read_b128 v[210:213], v153 offset:55296
	ds_read_b128 v[214:217], v153 offset:56320
	global_load_lds_dwordx4 v[218:219], off
	s_add_i32 m0, s26, 0x2000
	s_add_u32 s24, s24, 0xb0080
	v_lshl_add_u64 v[218:219], v[220:221], 0, s[16:17]
	s_addc_u32 s25, s25, 0
	s_add_i32 s26, s50, s28
	global_load_lds_dwordx4 v[218:219], off
	v_lshl_add_u64 v[218:219], s[24:25], 0, v[130:131]
	s_mov_b32 m0, s26
	s_nop 0
	global_load_lds_dwordx4 v[218:219], off
	v_lshl_add_u64 v[218:219], s[24:25], 0, v[134:135]
	s_add_i32 m0, s26, 0x2000
	s_nop 0
	global_load_lds_dwordx4 v[218:219], off
	v_lshl_add_u64 v[218:219], v[222:223], 0, s[16:17]
	s_mov_b32 m0, s37
	s_nop 0
	global_load_lds_dwordx4 v[218:219], off
	v_lshl_add_u64 v[218:219], v[224:225], 0, s[16:17]
	s_mov_b32 m0, s38
	s_nop 0
	global_load_lds_dwordx4 v[218:219], off
	s_waitcnt vmcnt(8)
	s_waitcnt lgkmcnt(0)
	s_barrier
	s_setprio 1
	s_waitcnt lgkmcnt(0)
	v_mfma_f32_16x16x32_bf16 v[60:63], v[144:147], v[184:187], v[60:63]
	v_mfma_f32_16x16x32_bf16 v[56:59], v[160:163], v[184:187], v[56:59]
	v_mfma_f32_16x16x32_bf16 v[44:47], v[144:147], v[192:195], v[44:47]
	v_mfma_f32_16x16x32_bf16 v[40:43], v[160:163], v[192:195], v[40:43]
	v_mfma_f32_16x16x32_bf16 v[28:31], v[144:147], v[202:205], v[28:31]
	v_mfma_f32_16x16x32_bf16 v[24:27], v[160:163], v[202:205], v[24:27]
	v_mfma_f32_16x16x32_bf16 v[12:15], v[144:147], v[210:213], v[12:15]
	v_mfma_f32_16x16x32_bf16 v[8:11], v[160:163], v[210:213], v[8:11]
	v_mfma_f32_16x16x32_bf16 v[60:63], v[156:159], v[188:191], v[60:63]
	v_mfma_f32_16x16x32_bf16 v[56:59], v[164:167], v[188:191], v[56:59]
	v_mfma_f32_16x16x32_bf16 v[44:47], v[156:159], v[198:201], v[44:47]
	v_mfma_f32_16x16x32_bf16 v[40:43], v[164:167], v[198:201], v[40:43]
	v_mfma_f32_16x16x32_bf16 v[28:31], v[156:159], v[206:209], v[28:31]
	v_mfma_f32_16x16x32_bf16 v[24:27], v[164:167], v[206:209], v[24:27]
	v_mfma_f32_16x16x32_bf16 v[12:15], v[156:159], v[214:217], v[12:15]
	v_mfma_f32_16x16x32_bf16 v[8:11], v[164:167], v[214:217], v[8:11]
	s_setprio 0
	s_setprio 1
	v_mfma_f32_16x16x32_bf16 v[52:55], v[168:171], v[184:187], v[52:55]
	v_mfma_f32_16x16x32_bf16 v[48:51], v[176:179], v[184:187], v[48:51]
	v_mfma_f32_16x16x32_bf16 v[36:39], v[168:171], v[192:195], v[36:39]
	v_mfma_f32_16x16x32_bf16 v[32:35], v[176:179], v[192:195], v[32:35]
	v_mfma_f32_16x16x32_bf16 v[20:23], v[168:171], v[202:205], v[20:23]
	v_mfma_f32_16x16x32_bf16 v[16:19], v[176:179], v[202:205], v[16:19]
	v_mfma_f32_16x16x32_bf16 v[4:7], v[168:171], v[210:213], v[4:7]
	v_mfma_f32_16x16x32_bf16 v[0:3], v[176:179], v[210:213], v[0:3]
	v_mfma_f32_16x16x32_bf16 v[52:55], v[172:175], v[188:191], v[52:55]
	v_mfma_f32_16x16x32_bf16 v[48:51], v[180:183], v[188:191], v[48:51]
	v_mfma_f32_16x16x32_bf16 v[36:39], v[172:175], v[198:201], v[36:39]
	v_mfma_f32_16x16x32_bf16 v[32:35], v[180:183], v[198:201], v[32:35]
	v_mfma_f32_16x16x32_bf16 v[20:23], v[172:175], v[206:209], v[20:23]
	v_mfma_f32_16x16x32_bf16 v[16:19], v[180:183], v[206:209], v[16:19]
	v_mfma_f32_16x16x32_bf16 v[4:7], v[172:175], v[214:217], v[4:7]
	v_mfma_f32_16x16x32_bf16 v[0:3], v[180:183], v[214:217], v[0:3]
	s_setprio 0
	s_barrier
	s_add_i32 s48, s48, 2
	s_add_u32 s22, s22, 0x100
	s_addc_u32 s23, s23, 0
	s_add_u32 s46, s46, 0x100
	s_addc_u32 s47, s47, 0
	s_cmp_gt_u32 s48, 41
	s_cbranch_scc0 .LBB0_370
	s_and_b64 vcc, exec, s[18:19]
	s_cbranch_vccz .LBB0_373
	s_barrier

; #define PG8_STAGE(bufoff, gbase, voff) do { _Pragma("unroll") for (int _i = 0; _i < 2; ++_i) \
;         __builtin_amdgcn_global_load_lds((const unsigned*)((const char*)(gbase) + (voff)[_i]), (PG8_LAS unsigned*)(lds + (bufoff) + ldsw + _i * 8192), 16, 0, 0); } while (0)
; #define PG8_LDA(dst, b, h) do { _Pragma("unroll") for (int m = 0; m < 4; ++m) _Pragma("unroll") for (int k = 0; k < 2; ++k) dst[m][k] = *(const PG8_LAS bf16x8*)(lds + PG8_SA(b, h) + aoff + m * 2048 + k * 1024); } while (0)
; #define PG8_LDB(dst, b, h) do { _Pragma("unroll") for (int n = 0; n < 2; ++n) _Pragma("unroll") for (int k = 0; k < 2; ++k) dst[n][k] = *(const PG8_LAS bf16x8*)(lds + PG8_SB(b, h) + boff + n * 2048 + k * 1024); } while (0)
; #define PG8_SCHED __builtin_amdgcn_sched_barrier(0)
; template <class Epi, class Sched, bool ALIGN_EPI = false, bool SP2 = false>
; __device__ __forceinline__ void gemm_phase(PG8_LAS unsigned char* lds, const Gemm g, const Sched& S, const Epi& E) {
;     ...
;         for (int t = 0; t < nt; t += 2) {
;             const bool last = (t == nt - 2);
;             const char* a1 = cA + (size_t)(t + 1) * kstep;
;             const char* a2 = last ? nA : cA + (size_t)(t + 2) * kstep; const char* b2 = last ? nB : cB + (size_t)(t + 2) * kstep;
;             const char* a3 = a2 + kstep; const char* b3 = b2 + kstep;
;             if (last && has_next) S.a_ready(nxt);
;             if constexpr (SP2) {
;             PG8_LDB(B0, 0, 0); PG8_LDB(B1, 0, 1); PG8_SCHED; PG8_LDA(At, 0, 0); PG8_STAGE(PG8_SA(1, 1), a1 + hstep, voffA);
;     ...
; #pragma unroll
;         for (int a = 0; a < 2; ++a)
; #pragma unroll
;             for (int b = 0; b < 2; ++b)
; #pragma unroll
;                 for (int m = 0; m < 4; ++m)
; #pragma unroll
;                     for (int n = 0; n < 2; ++n) acc[a][b][m][n] = (f32x4){0.f, 0.f, 0.f, 0.f};
.LBB0_524:
	s_ashr_i32 s23, s22, 31
	s_lshl_b64 s[24:25], s[22:23], 19
	s_add_u32 s24, s62, s24
	s_addc_u32 s25, s63, s25
	s_and_b64 s[26:27], s[0:1], exec
	s_cselect_b32 s3, s25, s31
	s_cselect_b32 s23, s24, s30
	s_ashr_i32 s21, s20, 31
	s_lshl_b64 s[26:27], s[20:21], 19
	s_add_u32 s26, s6, s26
	s_addc_u32 s27, s7, s27
	s_and_b64 s[36:37], s[0:1], exec
	s_cselect_b32 s21, s27, s35
	s_cselect_b32 s50, s26, s34
	s_add_u32 s30, s30, 0x40080
	s_addc_u32 s31, s31, 0
	s_add_u32 s51, s34, 0x100
	v_mov_b32_e32 v0, 0
	s_addc_u32 s52, s35, 0
	s_mov_b32 s53, -2
	ds_read_b128 v[144:147], v157
	ds_read_b128 v[148:151], v157 offset:1024
	ds_read_b128 v[162:165], v157 offset:2048
	ds_read_b128 v[166:169], v157 offset:3072
	ds_read_b128 v[170:173], v158
	ds_read_b128 v[174:177], v158 offset:1024
	ds_read_b128 v[178:181], v158 offset:2048
	ds_read_b128 v[182:185], v158 offset:3072
	s_add_u32 s34, s30, 0xfffc0080
	s_addc_u32 s35, s31, -1
	s_cmp_eq_u32 s53, 12
	s_cselect_b32 s37, s3, s35
	s_cselect_b32 s36, s23, s34
	s_cselect_b32 s35, s21, s52
	s_cselect_b32 s34, s50, s51
	v_lshl_add_u64 v[194:195], s[30:31], 0, v[136:137]
	s_add_i32 m0, s29, 0xc000
	ds_read_b128 v[186:189], v159
	ds_read_b128 v[190:193], v159 offset:1024
	ds_read_b128 v[198:201], v159 offset:2048
	ds_read_b128 v[202:205], v159 offset:3072
	ds_read_b128 v[206:209], v159 offset:4096
	ds_read_b128 v[210:213], v159 offset:5120
	ds_read_b128 v[214:217], v159 offset:6144
	ds_read_b128 v[218:221], v159 offset:7168
	v_mov_b32_e32 v1, v0
	v_mov_b32_e32 v2, v0
	v_mov_b32_e32 v3, v0
	v_mov_b32_e32 v4, v0
	v_mov_b32_e32 v5, v0
	v_mov_b32_e32 v6, v0
	v_mov_b32_e32 v7, v0
	v_mov_b32_e32 v8, v0
	v_mov_b32_e32 v9, v0
	v_mov_b32_e32 v10, v0
	v_mov_b32_e32 v11, v0
	v_mov_b32_e32 v12, v0
	v_mov_b32_e32 v13, v0
	v_mov_b32_e32 v14, v0
	v_mov_b32_e32 v15, v0
	v_mov_b32_e32 v16, v0
	v_mov_b32_e32 v17, v0
	v_mov_b32_e32 v18, v0
	v_mov_b32_e32 v19, v0
	v_mov_b32_e32 v20, v0
	v_mov_b32_e32 v21, v0
	v_mov_b32_e32 v22, v0
	v_mov_b32_e32 v23, v0
	v_mov_b32_e32 v24, v0
	v_mov_b32_e32 v25, v0
	v_mov_b32_e32 v26, v0
	v_mov_b32_e32 v27, v0
	v_mov_b32_e32 v28, v0
	v_mov_b32_e32 v29, v0
	v_mov_b32_e32 v30, v0
	v_mov_b32_e32 v31, v0
	v_mov_b32_e32 v60, v0
	v_mov_b32_e32 v61, v0
	v_mov_b32_e32 v62, v0
	v_mov_b32_e32 v63, v0
	v_mov_b32_e32 v68, v0
	v_mov_b32_e32 v69, v0
	v_mov_b32_e32 v70, v0
	v_mov_b32_e32 v71, v0
	v_mov_b32_e32 v72, v0
	v_mov_b32_e32 v73, v0
	v_mov_b32_e32 v74, v0
	v_mov_b32_e32 v75, v0
	v_mov_b32_e32 v76, v0
	v_mov_b32_e32 v77, v0
	v_mov_b32_e32 v78, v0
	v_mov_b32_e32 v79, v0
	v_mov_b32_e32 v80, v0
	v_mov_b32_e32 v81, v0
	v_mov_b32_e32 v82, v0
	v_mov_b32_e32 v83, v0
	v_mov_b32_e32 v84, v0
	v_mov_b32_e32 v85, v0
	v_mov_b32_e32 v86, v0
	v_mov_b32_e32 v87, v0
	v_mov_b32_e32 v88, v0
	v_mov_b32_e32 v89, v0
	v_mov_b32_e32 v90, v0
	v_mov_b32_e32 v91, v0
	v_mov_b32_e32 v92, v0
	v_mov_b32_e32 v93, v0
	v_mov_b32_e32 v94, v0
	v_mov_b32_e32 v95, v0
	v_mov_b32_e32 v32, v0
	v_mov_b32_e32 v33, v0
	v_mov_b32_e32 v34, v0
	v_mov_b32_e32 v35, v0
	v_mov_b32_e32 v36, v0
	v_mov_b32_e32 v37, v0
	v_mov_b32_e32 v38, v0
	v_mov_b32_e32 v39, v0
	v_mov_b32_e32 v40, v0
	v_mov_b32_e32 v41, v0
	v_mov_b32_e32 v42, v0
	v_mov_b32_e32 v43, v0
	v_mov_b32_e32 v44, v0
	v_mov_b32_e32 v45, v0
	v_mov_b32_e32 v46, v0
	v_mov_b32_e32 v47, v0
	v_mov_b32_e32 v48, v0
	v_mov_b32_e32 v49, v0
	v_mov_b32_e32 v50, v0
	v_mov_b32_e32 v51, v0
	v_mov_b32_e32 v52, v0
	v_mov_b32_e32 v53, v0
	v_mov_b32_e32 v54, v0
	v_mov_b32_e32 v55, v0
	v_mov_b32_e32 v56, v0
	v_mov_b32_e32 v57, v0
	v_mov_b32_e32 v58, v0
	v_mov_b32_e32 v59, v0
	v_mov_b32_e32 v64, v0
	v_mov_b32_e32 v65, v0
	v_mov_b32_e32 v66, v0
	v_mov_b32_e32 v67, v0
	v_mov_b32_e32 v96, v0
	v_mov_b32_e32 v97, v0
	v_mov_b32_e32 v98, v0
	v_mov_b32_e32 v99, v0
	v_mov_b32_e32 v100, v0
	v_mov_b32_e32 v101, v0
	v_mov_b32_e32 v102, v0
	v_mov_b32_e32 v103, v0
	v_mov_b32_e32 v104, v0
	v_mov_b32_e32 v105, v0
	v_mov_b32_e32 v106, v0
	v_mov_b32_e32 v107, v0
	v_mov_b32_e32 v108, v0
	v_mov_b32_e32 v109, v0
	v_mov_b32_e32 v110, v0
	v_mov_b32_e32 v111, v0
	v_mov_b32_e32 v112, v0
	v_mov_b32_e32 v113, v0
	v_mov_b32_e32 v114, v0
	v_mov_b32_e32 v115, v0
	v_mov_b32_e32 v116, v0
	v_mov_b32_e32 v117, v0
	v_mov_b32_e32 v118, v0
	v_mov_b32_e32 v119, v0
	v_mov_b32_e32 v120, v0
	v_mov_b32_e32 v121, v0
	v_mov_b32_e32 v122, v0
	v_mov_b32_e32 v123, v0
	v_mov_b32_e32 v124, v0
	v_mov_b32_e32 v125, v0
	v_mov_b32_e32 v126, v0
	v_mov_b32_e32 v127, v0
	v_lshl_add_u32 v246, s2, 8, v153
	v_ashrrev_i32_e32 v247, 31, v246
	v_lshl_add_u64 v[248:249], v[246:247], 2, s[4:5]
	global_load_dword v230, v[248:249], off
	global_load_dword v232, v[248:249], off offset:64
	global_load_dword v234, v[248:249], off offset:128
	global_load_dword v236, v[248:249], off offset:192
	global_load_dword v238, v[248:249], off offset:512
	global_load_dword v240, v[248:249], off offset:576
	global_load_dword v242, v[248:249], off offset:640
	global_load_dword v244, v[248:249], off offset:704
	s_cmp_eq_u32 s41, 1
	s_cselect_b32 s101, 0x7fffffff, -2
	s_branch .Lzh2_mid

; #define PG8_STAGE(bufoff, gbase, voff) do { _Pragma("unroll") for (int _i = 0; _i < 2; ++_i) \
;         __builtin_amdgcn_global_load_lds((const unsigned*)((const char*)(gbase) + (voff)[_i]), (PG8_LAS unsigned*)(lds + (bufoff) + ldsw + _i * 8192), 16, 0, 0); } while (0)
; #define PG8_LDA(dst, b, h) do { _Pragma("unroll") for (int m = 0; m < 4; ++m) _Pragma("unroll") for (int k = 0; k < 2; ++k) dst[m][k] = *(const PG8_LAS bf16x8*)(lds + PG8_SA(b, h) + aoff + m * 2048 + k * 1024); } while (0)
; #define PG8_LDB(dst, b, h) do { _Pragma("unroll") for (int n = 0; n < 2; ++n) _Pragma("unroll") for (int k = 0; k < 2; ++k) dst[n][k] = *(const PG8_LAS bf16x8*)(lds + PG8_SB(b, h) + boff + n * 2048 + k * 1024); } while (0)
; #define PG8_MMA(ai, bj, At, Bt) do { __builtin_amdgcn_s_setprio(1); _Pragma("unroll") for (int m = 0; m < 4; ++m) _Pragma("unroll") for (int n = 0; n < 2; ++n) _Pragma("unroll") for (int k = 0; k < 2; ++k) \
;         acc[ai][bj][m][n] = __builtin_amdgcn_mfma_f32_16x16x32_bf16(Bt[n][k], At[m][k], acc[ai][bj][m][n], 0, 0, 0); __builtin_amdgcn_s_setprio(0); } while (0)
; #define PG8_WAIT_V(n) asm volatile("s_waitcnt vmcnt(" #n ")" ::: "memory")
; #define PG8_WAIT_L(n) asm volatile("s_waitcnt lgkmcnt(" #n ")" ::: "memory")
; #define PG8_BAR __builtin_amdgcn_s_barrier()
; #define PG8_SCHED __builtin_amdgcn_sched_barrier(0)
; template <class Epi, class Sched, bool ALIGN_EPI = false, bool SP2 = false>
; __device__ __forceinline__ void gemm_phase(PG8_LAS unsigned char* lds, const Gemm g, const Sched& S, const Epi& E) {
;     ...
;             PG8_LDB(B0, 0, 0); PG8_LDB(B1, 0, 1); PG8_SCHED; PG8_LDA(At, 0, 0); PG8_STAGE(PG8_SA(1, 1), a1 + hstep, voffA);
;             PG8_WAIT_V(8); PG8_WAIT_L(0); PG8_BAR; PG8_MMA(0, 0, At, B0); PG8_MMA(0, 1, At, B1); PG8_BAR; PG8_SCHED;
.Lzh2_mid:
	global_load_lds_dwordx4 v[194:195], off
	v_lshl_add_u64 v[194:195], s[30:31], 0, v[138:139]
	s_add_i32 m0, s29, 0xe000
	s_nop 0
	global_load_lds_dwordx4 v[194:195], off
	s_cmp_eq_u32 s53, s101
	s_cbranch_scc1 .Lrw1_r0
	s_waitcnt vmcnt(8)

; #define PG8_STAGE(bufoff, gbase, voff) do { _Pragma("unroll") for (int _i = 0; _i < 2; ++_i) \
;         __builtin_amdgcn_global_load_lds((const unsigned*)((const char*)(gbase) + (voff)[_i]), (PG8_LAS unsigned*)(lds + (bufoff) + ldsw + _i * 8192), 16, 0, 0); } while (0)
; #define PG8_LDA(dst, b, h) do { _Pragma("unroll") for (int m = 0; m < 4; ++m) _Pragma("unroll") for (int k = 0; k < 2; ++k) dst[m][k] = *(const PG8_LAS bf16x8*)(lds + PG8_SA(b, h) + aoff + m * 2048 + k * 1024); } while (0)
; #define PG8_LDB(dst, b, h) do { _Pragma("unroll") for (int n = 0; n < 2; ++n) _Pragma("unroll") for (int k = 0; k < 2; ++k) dst[n][k] = *(const PG8_LAS bf16x8*)(lds + PG8_SB(b, h) + boff + n * 2048 + k * 1024); } while (0)
; #define PG8_SCHED __builtin_amdgcn_sched_barrier(0)
; template <class Epi, class Sched, bool ALIGN_EPI = false, bool SP2 = false>
; __device__ __forceinline__ void gemm_phase(PG8_LAS unsigned char* lds, const Gemm g, const Sched& S, const Epi& E) {
;     ...
;         for (int t = 0; t < nt; t += 2) {
;             const bool last = (t == nt - 2);
;             const char* a1 = cA + (size_t)(t + 1) * kstep;
;             const char* a2 = last ? nA : cA + (size_t)(t + 2) * kstep; const char* b2 = last ? nB : cB + (size_t)(t + 2) * kstep;
;             const char* a3 = a2 + kstep; const char* b3 = b2 + kstep;
;             if (last && has_next) S.a_ready(nxt);
;             if constexpr (SP2) {
;             PG8_LDB(B0, 0, 0); PG8_LDB(B1, 0, 1); PG8_SCHED; PG8_LDA(At, 0, 0); PG8_STAGE(PG8_SA(1, 1), a1 + hstep, voffA);
;     ...
; #pragma unroll
;         for (int a = 0; a < 2; ++a)
; #pragma unroll
;             for (int b = 0; b < 2; ++b)
; #pragma unroll
;                 for (int m = 0; m < 4; ++m)
; #pragma unroll
;                     for (int n = 0; n < 2; ++n) acc[a][b][m][n] = (f32x4){0.f, 0.f, 0.f, 0.f};
.LBB0_1145:
	s_ashr_i32 s19, s18, 31
	s_lshl_b64 s[20:21], s[18:19], 19
	s_add_u32 s20, s80, s20
	s_addc_u32 s21, s81, s21
	s_and_b64 s[22:23], s[0:1], exec
	s_cselect_b32 s3, s21, s27
	s_cselect_b32 s19, s20, s26
	s_ashr_i32 s17, s16, 31
	s_lshl_b64 s[22:23], s[16:17], 19
	s_add_u32 s22, s56, s22
	s_addc_u32 s23, s57, s23
	s_and_b64 s[30:31], s[0:1], exec
	s_cselect_b32 s17, s23, s29
	s_cselect_b32 s47, s22, s28
	s_add_u32 s26, s26, 0x40080
	s_addc_u32 s27, s27, 0
	s_add_u32 s48, s28, 0x100
	v_mov_b32_e32 v0, 0
	s_addc_u32 s49, s29, 0
	s_mov_b32 s50, -2
	ds_read_b128 v[144:147], v153
	ds_read_b128 v[156:159], v153 offset:1024
	ds_read_b128 v[160:163], v153 offset:2048
	ds_read_b128 v[164:167], v153 offset:3072
	ds_read_b128 v[168:171], v154
	ds_read_b128 v[172:175], v154 offset:1024
	ds_read_b128 v[176:179], v154 offset:2048
	ds_read_b128 v[180:183], v154 offset:3072
	s_add_u32 s28, s26, 0xfffc0080
	s_addc_u32 s29, s27, -1
	s_cmp_eq_u32 s50, 12
	s_cselect_b32 s31, s3, s29
	s_cselect_b32 s30, s19, s28
	s_cselect_b32 s29, s17, s49
	s_cselect_b32 s28, s47, s48
	v_lshl_add_u64 v[218:219], s[26:27], 0, v[136:137]
	s_add_i32 m0, s25, 0xc000
	ds_read_b128 v[184:187], v155
	ds_read_b128 v[188:191], v155 offset:1024
	ds_read_b128 v[192:195], v155 offset:2048
	ds_read_b128 v[198:201], v155 offset:3072
	ds_read_b128 v[202:205], v155 offset:4096
	ds_read_b128 v[206:209], v155 offset:5120
	ds_read_b128 v[210:213], v155 offset:6144
	ds_read_b128 v[214:217], v155 offset:7168
	v_mov_b32_e32 v1, v0
	v_mov_b32_e32 v2, v0
	v_mov_b32_e32 v3, v0
	v_mov_b32_e32 v8, v0
	v_mov_b32_e32 v9, v0
	v_mov_b32_e32 v10, v0
	v_mov_b32_e32 v11, v0
	v_mov_b32_e32 v16, v0
	v_mov_b32_e32 v17, v0
	v_mov_b32_e32 v18, v0
	v_mov_b32_e32 v19, v0
	v_mov_b32_e32 v24, v0
	v_mov_b32_e32 v25, v0
	v_mov_b32_e32 v26, v0
	v_mov_b32_e32 v27, v0
	v_mov_b32_e32 v32, v0
	v_mov_b32_e32 v33, v0
	v_mov_b32_e32 v34, v0
	v_mov_b32_e32 v35, v0
	v_mov_b32_e32 v40, v0
	v_mov_b32_e32 v41, v0
	v_mov_b32_e32 v42, v0
	v_mov_b32_e32 v43, v0
	v_mov_b32_e32 v48, v0
	v_mov_b32_e32 v49, v0
	v_mov_b32_e32 v50, v0
	v_mov_b32_e32 v51, v0
	v_mov_b32_e32 v56, v0
	v_mov_b32_e32 v57, v0
	v_mov_b32_e32 v58, v0
	v_mov_b32_e32 v59, v0
	v_mov_b32_e32 v4, v0
	v_mov_b32_e32 v5, v0
	v_mov_b32_e32 v6, v0
	v_mov_b32_e32 v7, v0
	v_mov_b32_e32 v12, v0
	v_mov_b32_e32 v13, v0
	v_mov_b32_e32 v14, v0
	v_mov_b32_e32 v15, v0
	v_mov_b32_e32 v20, v0
	v_mov_b32_e32 v21, v0
	v_mov_b32_e32 v22, v0
	v_mov_b32_e32 v23, v0
	v_mov_b32_e32 v28, v0
	v_mov_b32_e32 v29, v0
	v_mov_b32_e32 v30, v0
	v_mov_b32_e32 v31, v0
	v_mov_b32_e32 v36, v0
	v_mov_b32_e32 v37, v0
	v_mov_b32_e32 v38, v0
	v_mov_b32_e32 v39, v0
	v_mov_b32_e32 v44, v0
	v_mov_b32_e32 v45, v0
	v_mov_b32_e32 v46, v0
	v_mov_b32_e32 v47, v0
	v_mov_b32_e32 v52, v0
	v_mov_b32_e32 v53, v0
	v_mov_b32_e32 v54, v0
	v_mov_b32_e32 v55, v0
	v_mov_b32_e32 v60, v0
	v_mov_b32_e32 v61, v0
	v_mov_b32_e32 v62, v0
	v_mov_b32_e32 v63, v0
	v_mov_b32_e32 v64, v0
	v_mov_b32_e32 v65, v0
	v_mov_b32_e32 v66, v0
	v_mov_b32_e32 v67, v0
	v_mov_b32_e32 v72, v0
	v_mov_b32_e32 v73, v0
	v_mov_b32_e32 v74, v0
	v_mov_b32_e32 v75, v0
	v_mov_b32_e32 v80, v0
	v_mov_b32_e32 v81, v0
	v_mov_b32_e32 v82, v0
	v_mov_b32_e32 v83, v0
	v_mov_b32_e32 v88, v0
	v_mov_b32_e32 v89, v0
	v_mov_b32_e32 v90, v0
	v_mov_b32_e32 v91, v0
	v_mov_b32_e32 v96, v0
	v_mov_b32_e32 v97, v0
	v_mov_b32_e32 v98, v0
	v_mov_b32_e32 v99, v0
	v_mov_b32_e32 v104, v0
	v_mov_b32_e32 v105, v0
	v_mov_b32_e32 v106, v0
	v_mov_b32_e32 v107, v0
	v_mov_b32_e32 v112, v0
	v_mov_b32_e32 v113, v0
	v_mov_b32_e32 v114, v0
	v_mov_b32_e32 v115, v0
	v_mov_b32_e32 v120, v0
	v_mov_b32_e32 v121, v0
	v_mov_b32_e32 v122, v0
	v_mov_b32_e32 v123, v0
	v_mov_b32_e32 v68, v0
	v_mov_b32_e32 v69, v0
	v_mov_b32_e32 v70, v0
	v_mov_b32_e32 v71, v0
	v_mov_b32_e32 v76, v0
	v_mov_b32_e32 v77, v0
	v_mov_b32_e32 v78, v0
	v_mov_b32_e32 v79, v0
	v_mov_b32_e32 v84, v0
	v_mov_b32_e32 v85, v0
	v_mov_b32_e32 v86, v0
	v_mov_b32_e32 v87, v0
	v_mov_b32_e32 v92, v0
	v_mov_b32_e32 v93, v0
	v_mov_b32_e32 v94, v0
	v_mov_b32_e32 v95, v0
	v_mov_b32_e32 v100, v0
	v_mov_b32_e32 v101, v0
	v_mov_b32_e32 v102, v0
	v_mov_b32_e32 v103, v0
	v_mov_b32_e32 v108, v0
	v_mov_b32_e32 v109, v0
	v_mov_b32_e32 v110, v0
	v_mov_b32_e32 v111, v0
	v_mov_b32_e32 v116, v0
	v_mov_b32_e32 v117, v0
	v_mov_b32_e32 v118, v0
	v_mov_b32_e32 v119, v0
	v_mov_b32_e32 v124, v0
	v_mov_b32_e32 v125, v0
	v_mov_b32_e32 v126, v0
	v_mov_b32_e32 v127, v0
	v_lshl_add_u32 v246, s2, 8, v149
	v_ashrrev_i32_e32 v247, 31, v246
	v_lshl_add_u64 v[248:249], v[246:247], 2, s[4:5]
	global_load_dword v230, v[248:249], off
	global_load_dword v232, v[248:249], off offset:64
	global_load_dword v234, v[248:249], off offset:128
	global_load_dword v236, v[248:249], off offset:192
	global_load_dword v238, v[248:249], off offset:512
	global_load_dword v240, v[248:249], off offset:576
	global_load_dword v242, v[248:249], off offset:640
	global_load_dword v244, v[248:249], off offset:704
	s_cmp_eq_u32 s37, 1
	s_cselect_b32 s101, 0x7fffffff, -2
	s_branch .Lzh3_mid

; #define PG8_STAGE(bufoff, gbase, voff) do { _Pragma("unroll") for (int _i = 0; _i < 2; ++_i) \
;         __builtin_amdgcn_global_load_lds((const unsigned*)((const char*)(gbase) + (voff)[_i]), (PG8_LAS unsigned*)(lds + (bufoff) + ldsw + _i * 8192), 16, 0, 0); } while (0)
; #define PG8_LDA(dst, b, h) do { _Pragma("unroll") for (int m = 0; m < 4; ++m) _Pragma("unroll") for (int k = 0; k < 2; ++k) dst[m][k] = *(const PG8_LAS bf16x8*)(lds + PG8_SA(b, h) + aoff + m * 2048 + k * 1024); } while (0)
; #define PG8_LDB(dst, b, h) do { _Pragma("unroll") for (int n = 0; n < 2; ++n) _Pragma("unroll") for (int k = 0; k < 2; ++k) dst[n][k] = *(const PG8_LAS bf16x8*)(lds + PG8_SB(b, h) + boff + n * 2048 + k * 1024); } while (0)
; #define PG8_MMA(ai, bj, At, Bt) do { __builtin_amdgcn_s_setprio(1); _Pragma("unroll") for (int m = 0; m < 4; ++m) _Pragma("unroll") for (int n = 0; n < 2; ++n) _Pragma("unroll") for (int k = 0; k < 2; ++k) \
;         acc[ai][bj][m][n] = __builtin_amdgcn_mfma_f32_16x16x32_bf16(Bt[n][k], At[m][k], acc[ai][bj][m][n], 0, 0, 0); __builtin_amdgcn_s_setprio(0); } while (0)
; #define PG8_WAIT_V(n) asm volatile("s_waitcnt vmcnt(" #n ")" ::: "memory")
; #define PG8_WAIT_L(n) asm volatile("s_waitcnt lgkmcnt(" #n ")" ::: "memory")
; #define PG8_BAR __builtin_amdgcn_s_barrier()
; #define PG8_SCHED __builtin_amdgcn_sched_barrier(0)
; template <class Epi, class Sched, bool ALIGN_EPI = false, bool SP2 = false>
; __device__ __forceinline__ void gemm_phase(PG8_LAS unsigned char* lds, const Gemm g, const Sched& S, const Epi& E) {
;     ...
;             PG8_LDB(B0, 0, 0); PG8_LDB(B1, 0, 1); PG8_SCHED; PG8_LDA(At, 0, 0); PG8_STAGE(PG8_SA(1, 1), a1 + hstep, voffA);
;             PG8_WAIT_V(8); PG8_WAIT_L(0); PG8_BAR; PG8_MMA(0, 0, At, B0); PG8_MMA(0, 1, At, B1); PG8_BAR; PG8_SCHED;
.Lzh3_mid:
	global_load_lds_dwordx4 v[218:219], off
	v_lshl_add_u64 v[218:219], s[26:27], 0, v[138:139]
	s_add_i32 m0, s25, 0xe000
	s_nop 0
	global_load_lds_dwordx4 v[218:219], off
	s_cmp_eq_u32 s50, s101
	s_cbranch_scc1 .Lrw2_r0
	s_waitcnt vmcnt(8)

; #define PG8_STAGE(bufoff, gbase, voff) do { _Pragma("unroll") for (int _i = 0; _i < 2; ++_i) \
;         __builtin_amdgcn_global_load_lds((const unsigned*)((const char*)(gbase) + (voff)[_i]), (PG8_LAS unsigned*)(lds + (bufoff) + ldsw + _i * 8192), 16, 0, 0); } while (0)
; #define PG8_LDA(dst, b, h) do { _Pragma("unroll") for (int m = 0; m < 4; ++m) _Pragma("unroll") for (int k = 0; k < 2; ++k) dst[m][k] = *(const PG8_LAS bf16x8*)(lds + PG8_SA(b, h) + aoff + m * 2048 + k * 1024); } while (0)
; #define PG8_LDB(dst, b, h) do { _Pragma("unroll") for (int n = 0; n < 2; ++n) _Pragma("unroll") for (int k = 0; k < 2; ++k) dst[n][k] = *(const PG8_LAS bf16x8*)(lds + PG8_SB(b, h) + boff + n * 2048 + k * 1024); } while (0)
; #define PG8_SCHED __builtin_amdgcn_sched_barrier(0)
; template <class Epi, class Sched, bool ALIGN_EPI = false, bool SP2 = false>
; __device__ __forceinline__ void gemm_phase(PG8_LAS unsigned char* lds, const Gemm g, const Sched& S, const Epi& E) {
;     ...
;         for (int t = 0; t < nt; t += 2) {
;             const bool last = (t == nt - 2);
;             const char* a1 = cA + (size_t)(t + 1) * kstep;
;             const char* a2 = last ? nA : cA + (size_t)(t + 2) * kstep; const char* b2 = last ? nB : cB + (size_t)(t + 2) * kstep;
;             const char* a3 = a2 + kstep; const char* b3 = b2 + kstep;
;             if (last && has_next) S.a_ready(nxt);
;             if constexpr (SP2) {
;             PG8_LDB(B0, 0, 0); PG8_LDB(B1, 0, 1); PG8_SCHED; PG8_LDA(At, 0, 0); PG8_STAGE(PG8_SA(1, 1), a1 + hstep, voffA);
;     ...
; #pragma unroll
;         for (int a = 0; a < 2; ++a)
; #pragma unroll
;             for (int b = 0; b < 2; ++b)
; #pragma unroll
;                 for (int m = 0; m < 4; ++m)
; #pragma unroll
;                     for (int n = 0; n < 2; ++n) acc[a][b][m][n] = (f32x4){0.f, 0.f, 0.f, 0.f};
.LBB0_1238:
	s_add_u32 s18, s18, 0xb0080
	s_addc_u32 s19, s19, 0
	s_add_u32 s42, s20, 0x100
	v_mov_b32_e32 v0, 0
	s_addc_u32 s43, s21, 0
	s_mov_b32 s44, -2
	v_mov_b32_e32 v1, v0
	v_mov_b32_e32 v2, v0
	v_mov_b32_e32 v3, v0
	v_mov_b32_e32 v4, v0
	s_waitcnt lgkmcnt(0)
	ds_read_b128 v[144:147], v151
	ds_read_b128 v[156:159], v151 offset:1024
	ds_read_b128 v[160:163], v151 offset:2048
	ds_read_b128 v[164:167], v151 offset:3072
	ds_read_b128 v[168:171], v152
	ds_read_b128 v[172:175], v152 offset:1024
	ds_read_b128 v[176:179], v152 offset:2048
	ds_read_b128 v[180:183], v152 offset:3072
	s_add_u32 s20, s18, 0xfff50080
	s_addc_u32 s21, s19, -1
	s_cmp_eq_u32 s44, 40
	s_cselect_b32 s23, s5, s21
	s_cselect_b32 s22, s4, s20
	s_cselect_b32 s21, s17, s43
	s_cselect_b32 s20, s16, s42
	v_lshl_add_u64 v[218:219], s[18:19], 0, v[136:137]
	s_add_i32 m0, s25, 0xc000
	ds_read_b128 v[184:187], v153
	ds_read_b128 v[188:191], v153 offset:1024
	ds_read_b128 v[192:195], v153 offset:2048
	ds_read_b128 v[198:201], v153 offset:3072
	ds_read_b128 v[202:205], v153 offset:4096
	ds_read_b128 v[206:209], v153 offset:5120
	ds_read_b128 v[210:213], v153 offset:6144
	ds_read_b128 v[214:217], v153 offset:7168
	v_mov_b32_e32 v5, v0
	v_mov_b32_e32 v6, v0
	v_mov_b32_e32 v7, v0
	v_mov_b32_e32 v16, v0
	v_mov_b32_e32 v17, v0
	v_mov_b32_e32 v18, v0
	v_mov_b32_e32 v19, v0
	v_mov_b32_e32 v20, v0
	v_mov_b32_e32 v21, v0
	v_mov_b32_e32 v22, v0
	v_mov_b32_e32 v23, v0
	v_mov_b32_e32 v32, v0
	v_mov_b32_e32 v33, v0
	v_mov_b32_e32 v34, v0
	v_mov_b32_e32 v35, v0
	v_mov_b32_e32 v36, v0
	v_mov_b32_e32 v37, v0
	v_mov_b32_e32 v38, v0
	v_mov_b32_e32 v39, v0
	v_mov_b32_e32 v48, v0
	v_mov_b32_e32 v49, v0
	v_mov_b32_e32 v50, v0
	v_mov_b32_e32 v51, v0
	v_mov_b32_e32 v52, v0
	v_mov_b32_e32 v53, v0
	v_mov_b32_e32 v54, v0
	v_mov_b32_e32 v55, v0
	v_mov_b32_e32 v8, v0
	v_mov_b32_e32 v9, v0
	v_mov_b32_e32 v10, v0
	v_mov_b32_e32 v11, v0
	v_mov_b32_e32 v12, v0
	v_mov_b32_e32 v13, v0
	v_mov_b32_e32 v14, v0
	v_mov_b32_e32 v15, v0
	v_mov_b32_e32 v24, v0
	v_mov_b32_e32 v25, v0
	v_mov_b32_e32 v26, v0
	v_mov_b32_e32 v27, v0
	v_mov_b32_e32 v28, v0
	v_mov_b32_e32 v29, v0
	v_mov_b32_e32 v30, v0
	v_mov_b32_e32 v31, v0
	v_mov_b32_e32 v40, v0
	v_mov_b32_e32 v41, v0
	v_mov_b32_e32 v42, v0
	v_mov_b32_e32 v43, v0
	v_mov_b32_e32 v44, v0
	v_mov_b32_e32 v45, v0
	v_mov_b32_e32 v46, v0
	v_mov_b32_e32 v47, v0
	v_mov_b32_e32 v56, v0
	v_mov_b32_e32 v57, v0
	v_mov_b32_e32 v58, v0
	v_mov_b32_e32 v59, v0
	v_mov_b32_e32 v60, v0
	v_mov_b32_e32 v61, v0
	v_mov_b32_e32 v62, v0
	v_mov_b32_e32 v63, v0
	v_mov_b32_e32 v64, v0
	v_mov_b32_e32 v65, v0
	v_mov_b32_e32 v66, v0
	v_mov_b32_e32 v67, v0
	v_mov_b32_e32 v68, v0
	v_mov_b32_e32 v69, v0
	v_mov_b32_e32 v70, v0
	v_mov_b32_e32 v71, v0
	v_mov_b32_e32 v80, v0
	v_mov_b32_e32 v81, v0
	v_mov_b32_e32 v82, v0
	v_mov_b32_e32 v83, v0
	v_mov_b32_e32 v84, v0
	v_mov_b32_e32 v85, v0
	v_mov_b32_e32 v86, v0
	v_mov_b32_e32 v87, v0
	v_mov_b32_e32 v96, v0
	v_mov_b32_e32 v97, v0
	v_mov_b32_e32 v98, v0
	v_mov_b32_e32 v99, v0
	v_mov_b32_e32 v100, v0
	v_mov_b32_e32 v101, v0
	v_mov_b32_e32 v102, v0
	v_mov_b32_e32 v103, v0
	v_mov_b32_e32 v112, v0
	v_mov_b32_e32 v113, v0
	v_mov_b32_e32 v114, v0
	v_mov_b32_e32 v115, v0
	v_mov_b32_e32 v116, v0
	v_mov_b32_e32 v117, v0
	v_mov_b32_e32 v118, v0
	v_mov_b32_e32 v119, v0
	v_mov_b32_e32 v72, v0
	v_mov_b32_e32 v73, v0
	v_mov_b32_e32 v74, v0
	v_mov_b32_e32 v75, v0
	v_mov_b32_e32 v76, v0
	v_mov_b32_e32 v77, v0
	v_mov_b32_e32 v78, v0
	v_mov_b32_e32 v79, v0
	v_mov_b32_e32 v88, v0
	v_mov_b32_e32 v89, v0
	v_mov_b32_e32 v90, v0
	v_mov_b32_e32 v91, v0
	v_mov_b32_e32 v92, v0
	v_mov_b32_e32 v93, v0
	v_mov_b32_e32 v94, v0
	v_mov_b32_e32 v95, v0
	v_mov_b32_e32 v104, v0
	v_mov_b32_e32 v105, v0
	v_mov_b32_e32 v106, v0
	v_mov_b32_e32 v107, v0
	v_mov_b32_e32 v108, v0
	v_mov_b32_e32 v109, v0
	v_mov_b32_e32 v110, v0
	v_mov_b32_e32 v111, v0
	v_mov_b32_e32 v120, v0
	v_mov_b32_e32 v121, v0
	v_mov_b32_e32 v122, v0
	v_mov_b32_e32 v123, v0
	v_mov_b32_e32 v124, v0
	v_mov_b32_e32 v125, v0
	v_mov_b32_e32 v126, v0
	v_mov_b32_e32 v127, v0
	s_branch .Lzh4_mid

; #define PG8_STAGE(bufoff, gbase, voff) do { _Pragma("unroll") for (int _i = 0; _i < 2; ++_i) \
;         __builtin_amdgcn_global_load_lds((const unsigned*)((const char*)(gbase) + (voff)[_i]), (PG8_LAS unsigned*)(lds + (bufoff) + ldsw + _i * 8192), 16, 0, 0); } while (0)
; #define PG8_LDA(dst, b, h) do { _Pragma("unroll") for (int m = 0; m < 4; ++m) _Pragma("unroll") for (int k = 0; k < 2; ++k) dst[m][k] = *(const PG8_LAS bf16x8*)(lds + PG8_SA(b, h) + aoff + m * 2048 + k * 1024); } while (0)
; #define PG8_LDB(dst, b, h) do { _Pragma("unroll") for (int n = 0; n < 2; ++n) _Pragma("unroll") for (int k = 0; k < 2; ++k) dst[n][k] = *(const PG8_LAS bf16x8*)(lds + PG8_SB(b, h) + boff + n * 2048 + k * 1024); } while (0)
; #define PG8_MMA(ai, bj, At, Bt) do { __builtin_amdgcn_s_setprio(1); _Pragma("unroll") for (int m = 0; m < 4; ++m) _Pragma("unroll") for (int n = 0; n < 2; ++n) _Pragma("unroll") for (int k = 0; k < 2; ++k) \
;         acc[ai][bj][m][n] = __builtin_amdgcn_mfma_f32_16x16x32_bf16(Bt[n][k], At[m][k], acc[ai][bj][m][n], 0, 0, 0); __builtin_amdgcn_s_setprio(0); } while (0)
; #define PG8_WAIT_V(n) asm volatile("s_waitcnt vmcnt(" #n ")" ::: "memory")
; #define PG8_WAIT_L(n) asm volatile("s_waitcnt lgkmcnt(" #n ")" ::: "memory")
; #define PG8_BAR __builtin_amdgcn_s_barrier()
; #define PG8_SCHED __builtin_amdgcn_sched_barrier(0)
; template <class Epi, class Sched, bool ALIGN_EPI = false, bool SP2 = false>
; __device__ __forceinline__ void gemm_phase(PG8_LAS unsigned char* lds, const Gemm g, const Sched& S, const Epi& E) {
;     ...
;             PG8_LDB(B0, 0, 0); PG8_LDB(B1, 0, 1); PG8_SCHED; PG8_LDA(At, 0, 0); PG8_STAGE(PG8_SA(1, 1), a1 + hstep, voffA);
;             PG8_WAIT_V(8); PG8_WAIT_L(0); PG8_BAR; PG8_MMA(0, 0, At, B0); PG8_MMA(0, 1, At, B1); PG8_BAR; PG8_SCHED;
;             PG8_LDA(At, 0, 1); PG8_STAGE(PG8_SB(0, 0), b2, voffB); PG8_STAGE(PG8_SB(0, 1), b2 + hstep, voffB); PG8_STAGE(PG8_SA(0, 0), a2, voffA);
;             PG8_WAIT_V(8); PG8_WAIT_L(0); PG8_BAR; PG8_MMA(1, 0, At, B0); PG8_MMA(1, 1, At, B1); PG8_BAR; PG8_SCHED;
.Lzh4_mid:
	global_load_lds_dwordx4 v[218:219], off
	v_lshl_add_u64 v[218:219], s[18:19], 0, v[138:139]
	s_add_i32 m0, s25, 0xe000
	s_nop 0
	global_load_lds_dwordx4 v[218:219], off
	s_waitcnt vmcnt(8)
	s_waitcnt lgkmcnt(0)
	s_barrier
	s_setprio 1
	s_waitcnt lgkmcnt(0)
	v_mfma_f32_16x16x32_bf16 v[124:127], v[144:147], v[184:187], v[124:127]
	v_mfma_f32_16x16x32_bf16 v[120:123], v[160:163], v[184:187], v[120:123]
	v_mfma_f32_16x16x32_bf16 v[108:111], v[144:147], v[192:195], v[108:111]
	v_mfma_f32_16x16x32_bf16 v[104:107], v[160:163], v[192:195], v[104:107]
	v_mfma_f32_16x16x32_bf16 v[92:95], v[144:147], v[202:205], v[92:95]
	v_mfma_f32_16x16x32_bf16 v[88:91], v[160:163], v[202:205], v[88:91]
	v_mfma_f32_16x16x32_bf16 v[76:79], v[144:147], v[210:213], v[76:79]
	v_mfma_f32_16x16x32_bf16 v[72:75], v[160:163], v[210:213], v[72:75]
	v_mfma_f32_16x16x32_bf16 v[124:127], v[156:159], v[188:191], v[124:127]
	v_mfma_f32_16x16x32_bf16 v[120:123], v[164:167], v[188:191], v[120:123]
	v_mfma_f32_16x16x32_bf16 v[108:111], v[156:159], v[198:201], v[108:111]
	v_mfma_f32_16x16x32_bf16 v[104:107], v[164:167], v[198:201], v[104:107]
	v_mfma_f32_16x16x32_bf16 v[92:95], v[156:159], v[206:209], v[92:95]
	v_mfma_f32_16x16x32_bf16 v[88:91], v[164:167], v[206:209], v[88:91]
	v_mfma_f32_16x16x32_bf16 v[76:79], v[156:159], v[214:217], v[76:79]
	v_mfma_f32_16x16x32_bf16 v[72:75], v[164:167], v[214:217], v[72:75]
	s_setprio 0
	s_setprio 1
	v_mfma_f32_16x16x32_bf16 v[116:119], v[168:171], v[184:187], v[116:119]
	v_mfma_f32_16x16x32_bf16 v[112:115], v[176:179], v[184:187], v[112:115]
	v_mfma_f32_16x16x32_bf16 v[100:103], v[168:171], v[192:195], v[100:103]
	v_mfma_f32_16x16x32_bf16 v[96:99], v[176:179], v[192:195], v[96:99]
	v_mfma_f32_16x16x32_bf16 v[84:87], v[168:171], v[202:205], v[84:87]
	v_mfma_f32_16x16x32_bf16 v[80:83], v[176:179], v[202:205], v[80:83]
	v_mfma_f32_16x16x32_bf16 v[68:71], v[168:171], v[210:213], v[68:71]
	v_mfma_f32_16x16x32_bf16 v[64:67], v[176:179], v[210:213], v[64:67]
	v_mfma_f32_16x16x32_bf16 v[116:119], v[172:175], v[188:191], v[116:119]
	v_mfma_f32_16x16x32_bf16 v[112:115], v[180:183], v[188:191], v[112:115]
	v_mfma_f32_16x16x32_bf16 v[100:103], v[172:175], v[198:201], v[100:103]
	v_mfma_f32_16x16x32_bf16 v[96:99], v[180:183], v[198:201], v[96:99]
	v_mfma_f32_16x16x32_bf16 v[84:87], v[172:175], v[206:209], v[84:87]
	v_mfma_f32_16x16x32_bf16 v[80:83], v[180:183], v[206:209], v[80:83]
	v_mfma_f32_16x16x32_bf16 v[68:71], v[172:175], v[214:217], v[68:71]
	v_mfma_f32_16x16x32_bf16 v[64:67], v[180:183], v[214:217], v[64:67]
	s_setprio 0
	s_barrier
	s_add_i32 s45, s36, s24
	v_lshl_add_u64 v[218:219], s[20:21], 0, v[130:131]
	s_mov_b32 m0, s45
	ds_read_b128 v[184:187], v153 offset:16384
	ds_read_b128 v[188:191], v153 offset:17408
	ds_read_b128 v[192:195], v153 offset:18432
	ds_read_b128 v[198:201], v153 offset:19456
	ds_read_b128 v[202:205], v153 offset:20480
	ds_read_b128 v[206:209], v153 offset:21504
	ds_read_b128 v[210:213], v153 offset:22528
	ds_read_b128 v[214:217], v153 offset:23552
	global_load_lds_dwordx4 v[218:219], off
	s_add_i32 m0, s45, 0x2000
	s_add_u32 s46, s20, 0xb0000
	v_lshl_add_u64 v[220:221], s[20:21], 0, v[134:135]
	s_addc_u32 s47, s21, 0
	s_add_i32 s45, s37, s24
	global_load_lds_dwordx4 v[220:221], off
	v_lshl_add_u64 v[222:223], s[46:47], 0, v[130:131]
	s_mov_b32 m0, s45
	v_lshl_add_u64 v[224:225], s[22:23], 0, v[132:133]
	global_load_lds_dwordx4 v[222:223], off
	v_lshl_add_u64 v[222:223], s[46:47], 0, v[134:135]
	s_add_i32 m0, s45, 0x2000
	s_nop 0
	global_load_lds_dwordx4 v[222:223], off
	v_lshl_add_u64 v[222:223], s[22:23], 0, v[128:129]
	s_mov_b32 m0, s25
	s_nop 0
	global_load_lds_dwordx4 v[222:223], off
	s_mov_b32 m0, s26
	s_nop 0
	global_load_lds_dwordx4 v[224:225], off
	s_waitcnt vmcnt(8)
	s_waitcnt lgkmcnt(0)
	s_barrier
	s_setprio 1
	s_waitcnt lgkmcnt(0)
	v_mfma_f32_16x16x32_bf16 v[60:63], v[144:147], v[184:187], v[60:63]
	v_mfma_f32_16x16x32_bf16 v[56:59], v[160:163], v[184:187], v[56:59]
	v_mfma_f32_16x16x32_bf16 v[44:47], v[144:147], v[192:195], v[44:47]
	v_mfma_f32_16x16x32_bf16 v[40:43], v[160:163], v[192:195], v[40:43]
	v_mfma_f32_16x16x32_bf16 v[28:31], v[144:147], v[202:205], v[28:31]
	v_mfma_f32_16x16x32_bf16 v[24:27], v[160:163], v[202:205], v[24:27]
	v_mfma_f32_16x16x32_bf16 v[12:15], v[144:147], v[210:213], v[12:15]
	v_mfma_f32_16x16x32_bf16 v[8:11], v[160:163], v[210:213], v[8:11]
	v_mfma_f32_16x16x32_bf16 v[60:63], v[156:159], v[188:191], v[60:63]
	v_mfma_f32_16x16x32_bf16 v[56:59], v[164:167], v[188:191], v[56:59]
	v_mfma_f32_16x16x32_bf16 v[44:47], v[156:159], v[198:201], v[44:47]
	v_mfma_f32_16x16x32_bf16 v[40:43], v[164:167], v[198:201], v[40:43]
	v_mfma_f32_16x16x32_bf16 v[28:31], v[156:159], v[206:209], v[28:31]
	v_mfma_f32_16x16x32_bf16 v[24:27], v[164:167], v[206:209], v[24:27]
	v_mfma_f32_16x16x32_bf16 v[12:15], v[156:159], v[214:217], v[12:15]
	v_mfma_f32_16x16x32_bf16 v[8:11], v[164:167], v[214:217], v[8:11]
	s_setprio 0
	s_setprio 1
	v_mfma_f32_16x16x32_bf16 v[52:55], v[168:171], v[184:187], v[52:55]
	v_mfma_f32_16x16x32_bf16 v[48:51], v[176:179], v[184:187], v[48:51]
	v_mfma_f32_16x16x32_bf16 v[36:39], v[168:171], v[192:195], v[36:39]
	v_mfma_f32_16x16x32_bf16 v[32:35], v[176:179], v[192:195], v[32:35]
	v_mfma_f32_16x16x32_bf16 v[20:23], v[168:171], v[202:205], v[20:23]
	v_mfma_f32_16x16x32_bf16 v[16:19], v[176:179], v[202:205], v[16:19]
	v_mfma_f32_16x16x32_bf16 v[4:7], v[168:171], v[210:213], v[4:7]
	v_mfma_f32_16x16x32_bf16 v[0:3], v[176:179], v[210:213], v[0:3]
	v_mfma_f32_16x16x32_bf16 v[52:55], v[172:175], v[188:191], v[52:55]
	v_mfma_f32_16x16x32_bf16 v[48:51], v[180:183], v[188:191], v[48:51]
	v_mfma_f32_16x16x32_bf16 v[36:39], v[172:175], v[198:201], v[36:39]
	v_mfma_f32_16x16x32_bf16 v[32:35], v[180:183], v[198:201], v[32:35]
	v_mfma_f32_16x16x32_bf16 v[20:23], v[172:175], v[206:209], v[20:23]
	v_mfma_f32_16x16x32_bf16 v[16:19], v[180:183], v[206:209], v[16:19]
	v_mfma_f32_16x16x32_bf16 v[4:7], v[172:175], v[214:217], v[4:7]
	v_mfma_f32_16x16x32_bf16 v[0:3], v[180:183], v[214:217], v[0:3]
	s_setprio 0
	s_barrier
; #define PG8_STAGE(bufoff, gbase, voff) do { _Pragma("unroll") for (int _i = 0; _i < 2; ++_i) \
;         __builtin_amdgcn_global_load_lds((const unsigned*)((const char*)(gbase) + (voff)[_i]), (PG8_LAS unsigned*)(lds + (bufoff) + ldsw + _i * 8192), 16, 0, 0); } while (0)
; #define PG8_LDA(dst, b, h) do { _Pragma("unroll") for (int m = 0; m < 4; ++m) _Pragma("unroll") for (int k = 0; k < 2; ++k) dst[m][k] = *(const PG8_LAS bf16x8*)(lds + PG8_SA(b, h) + aoff + m * 2048 + k * 1024); } while (0)
; #define PG8_LDB(dst, b, h) do { _Pragma("unroll") for (int n = 0; n < 2; ++n) _Pragma("unroll") for (int k = 0; k < 2; ++k) dst[n][k] = *(const PG8_LAS bf16x8*)(lds + PG8_SB(b, h) + boff + n * 2048 + k * 1024); } while (0)
; #define PG8_MMA(ai, bj, At, Bt) do { __builtin_amdgcn_s_setprio(1); _Pragma("unroll") for (int m = 0; m < 4; ++m) _Pragma("unroll") for (int n = 0; n < 2; ++n) _Pragma("unroll") for (int k = 0; k < 2; ++k) \
;         acc[ai][bj][m][n] = __builtin_amdgcn_mfma_f32_16x16x32_bf16(Bt[n][k], At[m][k], acc[ai][bj][m][n], 0, 0, 0); __builtin_amdgcn_s_setprio(0); } while (0)
; #define PG8_WAIT_V(n) asm volatile("s_waitcnt vmcnt(" #n ")" ::: "memory")
; #define PG8_WAIT_L(n) asm volatile("s_waitcnt lgkmcnt(" #n ")" ::: "memory")
; #define PG8_BAR __builtin_amdgcn_s_barrier()
; #define PG8_SCHED __builtin_amdgcn_sched_barrier(0)
; template <class Epi, class Sched, bool ALIGN_EPI = false, bool SP2 = false>
; __device__ __forceinline__ void gemm_phase(PG8_LAS unsigned char* lds, const Gemm g, const Sched& S, const Epi& E) {
;     ...
;             PG8_LDB(B0, 1, 0); PG8_LDB(B1, 1, 1); PG8_SCHED; PG8_LDA(At, 1, 0); PG8_STAGE(PG8_SA(0, 1), a2 + hstep, voffA);
;             PG8_WAIT_V(8); PG8_WAIT_L(0); PG8_BAR; PG8_MMA(0, 0, At, B0); PG8_MMA(0, 1, At, B1); PG8_BAR; PG8_SCHED;
	s_add_i32 s45, 0, 0x18000
	v_add_u32_e32 v155, s45, v149
	s_add_i32 s46, 0, 0x1c000
	ds_read_b128 v[144:147], v155
	ds_read_b128 v[156:159], v155 offset:1024
	ds_read_b128 v[160:163], v155 offset:2048
	ds_read_b128 v[164:167], v155 offset:3072
	v_add_u32_e32 v155, s46, v149
	ds_read_b128 v[168:171], v155
	ds_read_b128 v[172:175], v155 offset:1024
	ds_read_b128 v[176:179], v155 offset:2048
	ds_read_b128 v[180:183], v155 offset:3072
	s_add_u32 s22, s22, 0xb0000
	s_addc_u32 s23, s23, 0
	s_mov_b32 m0, s27
	v_lshl_add_u64 v[226:227], s[22:23], 0, v[128:129]
	ds_read_b128 v[184:187], v153 offset:32768
	ds_read_b128 v[188:191], v153 offset:33792
	ds_read_b128 v[192:195], v153 offset:34816
	ds_read_b128 v[198:201], v153 offset:35840
	ds_read_b128 v[202:205], v153 offset:36864
	ds_read_b128 v[206:209], v153 offset:37888
	ds_read_b128 v[210:213], v153 offset:38912
	ds_read_b128 v[214:217], v153 offset:39936
	global_load_lds_dwordx4 v[226:227], off
	v_lshl_add_u64 v[226:227], s[22:23], 0, v[132:133]
	s_mov_b32 m0, s28
	s_nop 0
	global_load_lds_dwordx4 v[226:227], off
	s_waitcnt vmcnt(8)
	s_waitcnt lgkmcnt(0)
	s_barrier
	s_setprio 1
	s_waitcnt lgkmcnt(0)
	v_mfma_f32_16x16x32_bf16 v[124:127], v[144:147], v[184:187], v[124:127]
	v_mfma_f32_16x16x32_bf16 v[120:123], v[160:163], v[184:187], v[120:123]
	v_mfma_f32_16x16x32_bf16 v[108:111], v[144:147], v[192:195], v[108:111]
	v_mfma_f32_16x16x32_bf16 v[104:107], v[160:163], v[192:195], v[104:107]
	v_mfma_f32_16x16x32_bf16 v[92:95], v[144:147], v[202:205], v[92:95]
	v_mfma_f32_16x16x32_bf16 v[88:91], v[160:163], v[202:205], v[88:91]
	v_mfma_f32_16x16x32_bf16 v[76:79], v[144:147], v[210:213], v[76:79]
	v_mfma_f32_16x16x32_bf16 v[72:75], v[160:163], v[210:213], v[72:75]
	v_mfma_f32_16x16x32_bf16 v[124:127], v[156:159], v[188:191], v[124:127]
	v_mfma_f32_16x16x32_bf16 v[120:123], v[164:167], v[188:191], v[120:123]
	v_mfma_f32_16x16x32_bf16 v[108:111], v[156:159], v[198:201], v[108:111]
	v_mfma_f32_16x16x32_bf16 v[104:107], v[164:167], v[198:201], v[104:107]
	v_mfma_f32_16x16x32_bf16 v[92:95], v[156:159], v[206:209], v[92:95]
	v_mfma_f32_16x16x32_bf16 v[88:91], v[164:167], v[206:209], v[88:91]
	v_mfma_f32_16x16x32_bf16 v[76:79], v[156:159], v[214:217], v[76:79]
	v_mfma_f32_16x16x32_bf16 v[72:75], v[164:167], v[214:217], v[72:75]
	s_setprio 0
	s_setprio 1
	v_mfma_f32_16x16x32_bf16 v[116:119], v[168:171], v[184:187], v[116:119]
	v_mfma_f32_16x16x32_bf16 v[112:115], v[176:179], v[184:187], v[112:115]
	v_mfma_f32_16x16x32_bf16 v[100:103], v[168:171], v[192:195], v[100:103]
	v_mfma_f32_16x16x32_bf16 v[96:99], v[176:179], v[192:195], v[96:99]
	v_mfma_f32_16x16x32_bf16 v[84:87], v[168:171], v[202:205], v[84:87]
	v_mfma_f32_16x16x32_bf16 v[80:83], v[176:179], v[202:205], v[80:83]
	v_mfma_f32_16x16x32_bf16 v[68:71], v[168:171], v[210:213], v[68:71]
	v_mfma_f32_16x16x32_bf16 v[64:67], v[176:179], v[210:213], v[64:67]
	v_mfma_f32_16x16x32_bf16 v[116:119], v[172:175], v[188:191], v[116:119]
	v_mfma_f32_16x16x32_bf16 v[112:115], v[180:183], v[188:191], v[112:115]
	v_mfma_f32_16x16x32_bf16 v[100:103], v[172:175], v[198:201], v[100:103]
	v_mfma_f32_16x16x32_bf16 v[96:99], v[180:183], v[198:201], v[96:99]
	v_mfma_f32_16x16x32_bf16 v[84:87], v[172:175], v[206:209], v[84:87]
	v_mfma_f32_16x16x32_bf16 v[80:83], v[180:183], v[206:209], v[80:83]
	v_mfma_f32_16x16x32_bf16 v[68:71], v[172:175], v[214:217], v[68:71]
	v_mfma_f32_16x16x32_bf16 v[64:67], v[180:183], v[214:217], v[64:67]
	s_setprio 0
	s_barrier
; #define PG8_STAGE(bufoff, gbase, voff) do { _Pragma("unroll") for (int _i = 0; _i < 2; ++_i) \
;         __builtin_amdgcn_global_load_lds((const unsigned*)((const char*)(gbase) + (voff)[_i]), (PG8_LAS unsigned*)(lds + (bufoff) + ldsw + _i * 8192), 16, 0, 0); } while (0)
; #define PG8_LDA(dst, b, h) do { _Pragma("unroll") for (int m = 0; m < 4; ++m) _Pragma("unroll") for (int k = 0; k < 2; ++k) dst[m][k] = *(const PG8_LAS bf16x8*)(lds + PG8_SA(b, h) + aoff + m * 2048 + k * 1024); } while (0)
; #define PG8_MMA(ai, bj, At, Bt) do { __builtin_amdgcn_s_setprio(1); _Pragma("unroll") for (int m = 0; m < 4; ++m) _Pragma("unroll") for (int n = 0; n < 2; ++n) _Pragma("unroll") for (int k = 0; k < 2; ++k) \
;         acc[ai][bj][m][n] = __builtin_amdgcn_mfma_f32_16x16x32_bf16(Bt[n][k], At[m][k], acc[ai][bj][m][n], 0, 0, 0); __builtin_amdgcn_s_setprio(0); } while (0)
; #define PG8_WAIT_V(n) asm volatile("s_waitcnt vmcnt(" #n ")" ::: "memory")
; #define PG8_WAIT_L(n) asm volatile("s_waitcnt lgkmcnt(" #n ")" ::: "memory")
; #define PG8_BAR __builtin_amdgcn_s_barrier()
; #define PG8_SCHED __builtin_amdgcn_sched_barrier(0)
; template <class Epi, class Sched, bool ALIGN_EPI = false, bool SP2 = false>
; __device__ __forceinline__ void gemm_phase(PG8_LAS unsigned char* lds, const Gemm g, const Sched& S, const Epi& E) {
;     ...
;             PG8_LDA(At, 1, 1); PG8_STAGE(PG8_SB(1, 0), b3, voffB); PG8_STAGE(PG8_SB(1, 1), b3 + hstep, voffB); PG8_STAGE(PG8_SA(1, 0), a3, voffA);
;             PG8_WAIT_V(8); PG8_WAIT_L(0); PG8_BAR; PG8_MMA(1, 0, At, B0); PG8_MMA(1, 1, At, B1); PG8_BAR; PG8_SCHED;
;     ...
;         if constexpr (ALIGN_EPI) { if (wr == 0) PG8_BAR; }
	s_add_i32 s22, s45, s24
	v_lshl_add_u64 v[218:219], v[218:219], 0, s[12:13]
	s_mov_b32 m0, s22
	ds_read_b128 v[184:187], v153 offset:49152
	ds_read_b128 v[188:191], v153 offset:50176
	ds_read_b128 v[192:195], v153 offset:51200
	ds_read_b128 v[198:201], v153 offset:52224
	ds_read_b128 v[202:205], v153 offset:53248
	ds_read_b128 v[206:209], v153 offset:54272
	ds_read_b128 v[210:213], v153 offset:55296
	ds_read_b128 v[214:217], v153 offset:56320
	global_load_lds_dwordx4 v[218:219], off
	s_add_i32 m0, s22, 0x2000
	s_add_u32 s20, s20, 0xb0080
	v_lshl_add_u64 v[218:219], v[220:221], 0, s[12:13]
	s_addc_u32 s21, s21, 0
	s_add_i32 s22, s46, s24
	global_load_lds_dwordx4 v[218:219], off
	v_lshl_add_u64 v[218:219], s[20:21], 0, v[130:131]
	s_mov_b32 m0, s22
	s_nop 0
	global_load_lds_dwordx4 v[218:219], off
	v_lshl_add_u64 v[218:219], s[20:21], 0, v[134:135]
	s_add_i32 m0, s22, 0x2000
	s_nop 0
	global_load_lds_dwordx4 v[218:219], off
	v_lshl_add_u64 v[218:219], v[222:223], 0, s[12:13]
	s_mov_b32 m0, s33
	s_nop 0
	global_load_lds_dwordx4 v[218:219], off
	v_lshl_add_u64 v[218:219], v[224:225], 0, s[12:13]
	s_mov_b32 m0, s34
	s_nop 0
	global_load_lds_dwordx4 v[218:219], off
	s_waitcnt vmcnt(8)
	s_waitcnt lgkmcnt(0)
	s_barrier
	s_setprio 1
	s_waitcnt lgkmcnt(0)
	v_mfma_f32_16x16x32_bf16 v[60:63], v[144:147], v[184:187], v[60:63]
	v_mfma_f32_16x16x32_bf16 v[56:59], v[160:163], v[184:187], v[56:59]
	v_mfma_f32_16x16x32_bf16 v[44:47], v[144:147], v[192:195], v[44:47]
	v_mfma_f32_16x16x32_bf16 v[40:43], v[160:163], v[192:195], v[40:43]
	v_mfma_f32_16x16x32_bf16 v[28:31], v[144:147], v[202:205], v[28:31]
	v_mfma_f32_16x16x32_bf16 v[24:27], v[160:163], v[202:205], v[24:27]
	v_mfma_f32_16x16x32_bf16 v[12:15], v[144:147], v[210:213], v[12:15]
	v_mfma_f32_16x16x32_bf16 v[8:11], v[160:163], v[210:213], v[8:11]
	v_mfma_f32_16x16x32_bf16 v[60:63], v[156:159], v[188:191], v[60:63]
	v_mfma_f32_16x16x32_bf16 v[56:59], v[164:167], v[188:191], v[56:59]
	v_mfma_f32_16x16x32_bf16 v[44:47], v[156:159], v[198:201], v[44:47]
	v_mfma_f32_16x16x32_bf16 v[40:43], v[164:167], v[198:201], v[40:43]
	v_mfma_f32_16x16x32_bf16 v[28:31], v[156:159], v[206:209], v[28:31]
	v_mfma_f32_16x16x32_bf16 v[24:27], v[164:167], v[206:209], v[24:27]
	v_mfma_f32_16x16x32_bf16 v[12:15], v[156:159], v[214:217], v[12:15]
	v_mfma_f32_16x16x32_bf16 v[8:11], v[164:167], v[214:217], v[8:11]
	s_setprio 0
	s_setprio 1
	v_mfma_f32_16x16x32_bf16 v[52:55], v[168:171], v[184:187], v[52:55]
	v_mfma_f32_16x16x32_bf16 v[48:51], v[176:179], v[184:187], v[48:51]
	v_mfma_f32_16x16x32_bf16 v[36:39], v[168:171], v[192:195], v[36:39]
	v_mfma_f32_16x16x32_bf16 v[32:35], v[176:179], v[192:195], v[32:35]
	v_mfma_f32_16x16x32_bf16 v[20:23], v[168:171], v[202:205], v[20:23]
	v_mfma_f32_16x16x32_bf16 v[16:19], v[176:179], v[202:205], v[16:19]
	v_mfma_f32_16x16x32_bf16 v[4:7], v[168:171], v[210:213], v[4:7]
	v_mfma_f32_16x16x32_bf16 v[0:3], v[176:179], v[210:213], v[0:3]
	v_mfma_f32_16x16x32_bf16 v[52:55], v[172:175], v[188:191], v[52:55]
	v_mfma_f32_16x16x32_bf16 v[48:51], v[180:183], v[188:191], v[48:51]
	v_mfma_f32_16x16x32_bf16 v[36:39], v[172:175], v[198:201], v[36:39]
	v_mfma_f32_16x16x32_bf16 v[32:35], v[180:183], v[198:201], v[32:35]
	v_mfma_f32_16x16x32_bf16 v[20:23], v[172:175], v[206:209], v[20:23]
	v_mfma_f32_16x16x32_bf16 v[16:19], v[180:183], v[206:209], v[16:19]
	v_mfma_f32_16x16x32_bf16 v[4:7], v[172:175], v[214:217], v[4:7]
	v_mfma_f32_16x16x32_bf16 v[0:3], v[180:183], v[214:217], v[0:3]
	s_setprio 0
	s_barrier
	s_add_i32 s44, s44, 2
	s_add_u32 s18, s18, 0x100
	s_addc_u32 s19, s19, 0
	s_add_u32 s42, s42, 0x100
	s_addc_u32 s43, s43, 0
	s_cmp_gt_u32 s44, 41
	s_cbranch_scc0 .LBB0_1239
	s_and_b64 vcc, exec, s[14:15]
	s_cbranch_vccz .LBB0_1242
	s_barrier
